# scanner loop body: 2 value rows per lane (16 lanes x 4 k), half the LDS reads, merged y reduction; plus v17 contents
# speedup vs baseline: 1.0050x; 1.0017x over previous
; #define LAS __attribute__((address_space(3)))
; __device__ __forceinline__ void rwkv_scan_phase(Frame& F, const bf16* RKV, const float* WAG, const bf16* AGB, const float* k_k, const float* k_a, const float* r_k, bf16* Y, float* BS, float* ST2) {
;     ...
;             const int row = lane >> 3, kg = lane & 7, vr = 8 * wave + row;
;             typedef float f32x2 __attribute__((ext_vector_type(2)));
;             f32x2 s[4];
; #pragma unroll
;             for (int i = 0; i < 4; ++i) s[i] = (f32x2){0.f, 0.f};
;             __syncthreads();
;             for (int ci = 0; ci < SEQ / SC_T; ++ci) {
;                 const LAS unsigned char* bp = F.lds + (ci & 1) * SC_BUF; LAS float* yb = (LAS float*)(F.lds + SC_YOFF + (ci & 1) * SC_YB);
;     ...
;                 f32x2 r0[4], w0[4], k0[4], a0[4], b0[4], r1[4], w1[4], k1[4], a1[4], b1[4]; float v0, v1;
;                 SC_LOAD(r0, w0, k0, a0, b0, v0, 0);
; #pragma unroll
;                 for (int t = 0; t < SC_T; t += 2) {
;                     SC_LOAD(r1, w1, k1, a1, b1, v1, t + 1);
;                     SC_STEP(r0, w0, k0, a0, b0, v0, t);
;                     if (t + 2 < SC_T) SC_LOAD(r0, w0, k0, a0, b0, v0, t + 2);
;                     SC_STEP(r1, w1, k1, a1, b1, v1, t + 1);
;                 }
.LBB0_1692:
	s_and_b32 s6, s0, 1
	s_mul_i32 s7, s6, 0xb000
	s_lshl_b32 s6, s6, 12
	v_mbcnt_lo_u32_b32 v130, -1, 0
	v_mbcnt_hi_u32_b32 v130, -1, v130
	v_and_b32_e32 v77, 15, v130
	v_lshl_add_u32 v74, v77, 4, s7
	v_lshrrev_b32_e32 v75, 4, v130
	v_lshl_add_u32 v75, s80, 2, v75
	v_lshlrev_b32_e32 v75, 3, v75
	v_lshl_add_u32 v76, v77, 2, v75
	v_add_u32_e32 v76, 0x16000, v76
	v_add_u32_e32 v75, s7, v75
	v_lshlrev_b32_e32 v6, 2, v130
	v_add_u32_e32 v6, 0x18000, v6
	v_cmp_gt_u32_e32 vcc, 2, v77
	s_nop 1
	v_cndmask_b32_e32 v76, v6, v76, vcc
	v_add_u32_e32 v76, s6, v76
	s_mov_b32 vcc_lo, 0xaaaaaaaa
	s_mov_b32 vcc_hi, 0xaaaaaaaa
	ds_read_b128 v[28:31], v74 offset:24576
	ds_read_b128 v[32:35], v74 offset:8192
	ds_read_b128 v[36:39], v74 offset:16384
	ds_read_b128 v[40:43], v74 offset:32768
	ds_read_b128 v[44:47], v74 offset:0
	ds_read_b64 v[48:49], v75 offset:40960
	ds_read_b128 v[106:109], v74 offset:24832
	ds_read_b128 v[110:113], v74 offset:8448
	ds_read_b128 v[114:117], v74 offset:16640
	ds_read_b128 v[118:121], v74 offset:33024
	ds_read_b128 v[122:125], v74 offset:256
	ds_read_b64 v[126:127], v75 offset:41088
	s_waitcnt lgkmcnt(6)
	v_pk_mul_f32 v[0:1], v[8:9], v[28:29] op_sel_hi:[1,0]
	v_pk_mul_f32 v[2:3], v[10:11], v[28:29] op_sel:[0,1]
	v_pk_fma_f32 v[0:1], v[20:21], v[30:31], v[0:1] op_sel_hi:[1,0,1]
	v_pk_fma_f32 v[2:3], v[22:23], v[30:31], v[2:3] op_sel:[0,1,0]
	v_pk_mul_f32 v[12:13], v[8:9], v[32:33] op_sel_hi:[1,0]
	v_pk_add_f32 v[0:1], v[0:1], v[2:3]
	v_pk_mul_f32 v[14:15], v[10:11], v[32:33] op_sel:[0,1]
	v_pk_mul_f32 v[16:17], v[20:21], v[34:35] op_sel_hi:[1,0]
	v_pk_mul_f32 v[18:19], v[22:23], v[34:35] op_sel:[0,1]
	v_add_f32_dpp v0, v0, v0 quad_perm:[1,0,3,2] row_mask:0xf bank_mask:0xf bound_ctrl:1
	v_add_f32_dpp v1, v1, v1 quad_perm:[1,0,3,2] row_mask:0xf bank_mask:0xf bound_ctrl:1
	v_pk_fma_f32 v[12:13], v[36:37], v[48:49], v[12:13] op_sel_hi:[0,1,1]
	v_pk_fma_f32 v[14:15], v[36:37], v[48:49], v[14:15] op_sel:[1,0,0]
	v_add_f32_dpp v0, v0, v0 quad_perm:[2,3,0,1] row_mask:0xf bank_mask:0xf bound_ctrl:1
	v_add_f32_dpp v1, v1, v1 quad_perm:[2,3,0,1] row_mask:0xf bank_mask:0xf bound_ctrl:1
	v_pk_fma_f32 v[16:17], v[38:39], v[48:49], v[16:17] op_sel_hi:[0,1,1]
	v_pk_fma_f32 v[18:19], v[38:39], v[48:49], v[18:19] op_sel:[1,0,0]
	v_add_f32_dpp v0, v0, v0 row_half_mirror row_mask:0xf bank_mask:0xf bound_ctrl:1
	v_add_f32_dpp v1, v1, v1 row_half_mirror row_mask:0xf bank_mask:0xf bound_ctrl:1
	s_nop 0
	v_add_f32_dpp v0, v0, v0 row_mirror row_mask:0xf bank_mask:0xf bound_ctrl:1
	v_add_f32_dpp v1, v1, v1 row_mirror row_mask:0xf bank_mask:0xf bound_ctrl:1
	v_pk_fma_f32 v[8:9], v[40:41], v[0:1], v[12:13] op_sel_hi:[0,1,1]
	v_pk_fma_f32 v[10:11], v[40:41], v[0:1], v[14:15] op_sel:[1,0,0]
	v_pk_fma_f32 v[20:21], v[42:43], v[0:1], v[16:17] op_sel_hi:[0,1,1]
	v_pk_fma_f32 v[22:23], v[42:43], v[0:1], v[18:19] op_sel:[1,0,0]
	v_pk_mul_f32 v[4:5], v[8:9], v[44:45] op_sel_hi:[1,0]
	v_pk_mul_f32 v[6:7], v[10:11], v[44:45] op_sel:[0,1]
	v_pk_fma_f32 v[4:5], v[20:21], v[46:47], v[4:5] op_sel_hi:[1,0,1]
	v_pk_fma_f32 v[6:7], v[22:23], v[46:47], v[6:7] op_sel:[0,1,0]
	ds_read_b128 v[28:31], v74 offset:25088
	ds_read_b128 v[32:35], v74 offset:8704
	ds_read_b128 v[36:39], v74 offset:16896
	ds_read_b128 v[40:43], v74 offset:33280
	ds_read_b128 v[44:47], v74 offset:512
	ds_read_b64 v[48:49], v75 offset:41216
	s_waitcnt lgkmcnt(6)
	v_pk_mul_f32 v[0:1], v[8:9], v[106:107] op_sel_hi:[1,0]
	v_pk_mul_f32 v[2:3], v[10:11], v[106:107] op_sel:[0,1]
	v_pk_fma_f32 v[0:1], v[20:21], v[108:109], v[0:1] op_sel_hi:[1,0,1]
	v_pk_fma_f32 v[2:3], v[22:23], v[108:109], v[2:3] op_sel:[0,1,0]
	v_pk_add_f32 v[4:5], v[4:5], v[6:7]
	v_pk_mul_f32 v[12:13], v[8:9], v[110:111] op_sel_hi:[1,0]
	v_pk_add_f32 v[0:1], v[0:1], v[2:3]
	v_pk_mul_f32 v[14:15], v[10:11], v[110:111] op_sel:[0,1]
	v_cndmask_b32_e32 v24, v4, v5, vcc
	v_cndmask_b32_e32 v25, v5, v4, vcc
	v_pk_mul_f32 v[16:17], v[20:21], v[112:113] op_sel_hi:[1,0]
	v_pk_mul_f32 v[18:19], v[22:23], v[112:113] op_sel:[0,1]
	v_add_f32_dpp v0, v0, v0 quad_perm:[1,0,3,2] row_mask:0xf bank_mask:0xf bound_ctrl:1
	v_add_f32_dpp v1, v1, v1 quad_perm:[1,0,3,2] row_mask:0xf bank_mask:0xf bound_ctrl:1
	v_add_f32_dpp v26, v25, v24 quad_perm:[1,0,3,2] row_mask:0xf bank_mask:0xf bound_ctrl:1
	v_pk_fma_f32 v[12:13], v[114:115], v[126:127], v[12:13] op_sel_hi:[0,1,1]
	v_pk_fma_f32 v[14:15], v[114:115], v[126:127], v[14:15] op_sel:[1,0,0]
	v_add_f32_dpp v0, v0, v0 quad_perm:[2,3,0,1] row_mask:0xf bank_mask:0xf bound_ctrl:1
	v_add_f32_dpp v1, v1, v1 quad_perm:[2,3,0,1] row_mask:0xf bank_mask:0xf bound_ctrl:1
	v_add_f32_dpp v26, v26, v26 quad_perm:[2,3,0,1] row_mask:0xf bank_mask:0xf bound_ctrl:1
	v_pk_fma_f32 v[16:17], v[116:117], v[126:127], v[16:17] op_sel_hi:[0,1,1]
	v_pk_fma_f32 v[18:19], v[116:117], v[126:127], v[18:19] op_sel:[1,0,0]
	v_add_f32_dpp v0, v0, v0 row_half_mirror row_mask:0xf bank_mask:0xf bound_ctrl:1
	v_add_f32_dpp v1, v1, v1 row_half_mirror row_mask:0xf bank_mask:0xf bound_ctrl:1
	v_add_f32_dpp v26, v26, v26 row_ror:4 row_mask:0xf bank_mask:0xf bound_ctrl:1
	s_nop 0
	v_add_f32_dpp v0, v0, v0 row_mirror row_mask:0xf bank_mask:0xf bound_ctrl:1
	v_add_f32_dpp v1, v1, v1 row_mirror row_mask:0xf bank_mask:0xf bound_ctrl:1
	v_add_f32_dpp v26, v26, v26 row_ror:8 row_mask:0xf bank_mask:0xf bound_ctrl:1
	ds_write_b32 v76, v26 offset:0
	v_pk_fma_f32 v[8:9], v[118:119], v[0:1], v[12:13] op_sel_hi:[0,1,1]
	v_pk_fma_f32 v[10:11], v[118:119], v[0:1], v[14:15] op_sel:[1,0,0]
	v_pk_fma_f32 v[20:21], v[120:121], v[0:1], v[16:17] op_sel_hi:[0,1,1]
	v_pk_fma_f32 v[22:23], v[120:121], v[0:1], v[18:19] op_sel:[1,0,0]
	v_pk_mul_f32 v[4:5], v[8:9], v[122:123] op_sel_hi:[1,0]
	v_pk_mul_f32 v[6:7], v[10:11], v[122:123] op_sel:[0,1]
	v_pk_fma_f32 v[4:5], v[20:21], v[124:125], v[4:5] op_sel_hi:[1,0,1]
	v_pk_fma_f32 v[6:7], v[22:23], v[124:125], v[6:7] op_sel:[0,1,0]
	ds_read_b128 v[106:109], v74 offset:25344
	ds_read_b128 v[110:113], v74 offset:8960
	ds_read_b128 v[114:117], v74 offset:17152
	ds_read_b128 v[118:121], v74 offset:33536
	ds_read_b128 v[122:125], v74 offset:768
	ds_read_b64 v[126:127], v75 offset:41344
	s_waitcnt lgkmcnt(7)
; __device__ __forceinline__ void rwkv_scan_phase(Frame& F, const bf16* RKV, const float* WAG, const bf16* AGB, const float* k_k, const float* k_a, const float* r_k, bf16* Y, float* BS, float* ST2) {
;     ...
;                 f32x2 r0[4], w0[4], k0[4], a0[4], b0[4], r1[4], w1[4], k1[4], a1[4], b1[4]; float v0, v1;
;                 SC_LOAD(r0, w0, k0, a0, b0, v0, 0);
; #pragma unroll
;                 for (int t = 0; t < SC_T; t += 2) {
;                     SC_LOAD(r1, w1, k1, a1, b1, v1, t + 1);
;                     SC_STEP(r0, w0, k0, a0, b0, v0, t);
;                     if (t + 2 < SC_T) SC_LOAD(r0, w0, k0, a0, b0, v0, t + 2);
;                     SC_STEP(r1, w1, k1, a1, b1, v1, t + 1);
;                 }
	v_pk_mul_f32 v[0:1], v[8:9], v[28:29] op_sel_hi:[1,0]
	v_pk_mul_f32 v[2:3], v[10:11], v[28:29] op_sel:[0,1]
	v_pk_fma_f32 v[0:1], v[20:21], v[30:31], v[0:1] op_sel_hi:[1,0,1]
	v_pk_fma_f32 v[2:3], v[22:23], v[30:31], v[2:3] op_sel:[0,1,0]
	v_pk_add_f32 v[4:5], v[4:5], v[6:7]
	v_pk_mul_f32 v[12:13], v[8:9], v[32:33] op_sel_hi:[1,0]
	v_pk_add_f32 v[0:1], v[0:1], v[2:3]
	v_pk_mul_f32 v[14:15], v[10:11], v[32:33] op_sel:[0,1]
	v_cndmask_b32_e32 v24, v4, v5, vcc
	v_cndmask_b32_e32 v25, v5, v4, vcc
	v_pk_mul_f32 v[16:17], v[20:21], v[34:35] op_sel_hi:[1,0]
	v_pk_mul_f32 v[18:19], v[22:23], v[34:35] op_sel:[0,1]
	v_add_f32_dpp v0, v0, v0 quad_perm:[1,0,3,2] row_mask:0xf bank_mask:0xf bound_ctrl:1
	v_add_f32_dpp v1, v1, v1 quad_perm:[1,0,3,2] row_mask:0xf bank_mask:0xf bound_ctrl:1
	v_add_f32_dpp v26, v25, v24 quad_perm:[1,0,3,2] row_mask:0xf bank_mask:0xf bound_ctrl:1
	v_pk_fma_f32 v[12:13], v[36:37], v[48:49], v[12:13] op_sel_hi:[0,1,1]
	v_pk_fma_f32 v[14:15], v[36:37], v[48:49], v[14:15] op_sel:[1,0,0]
	v_add_f32_dpp v0, v0, v0 quad_perm:[2,3,0,1] row_mask:0xf bank_mask:0xf bound_ctrl:1
	v_add_f32_dpp v1, v1, v1 quad_perm:[2,3,0,1] row_mask:0xf bank_mask:0xf bound_ctrl:1
	v_add_f32_dpp v26, v26, v26 quad_perm:[2,3,0,1] row_mask:0xf bank_mask:0xf bound_ctrl:1
	v_pk_fma_f32 v[16:17], v[38:39], v[48:49], v[16:17] op_sel_hi:[0,1,1]
	v_pk_fma_f32 v[18:19], v[38:39], v[48:49], v[18:19] op_sel:[1,0,0]
	v_add_f32_dpp v0, v0, v0 row_half_mirror row_mask:0xf bank_mask:0xf bound_ctrl:1
	v_add_f32_dpp v1, v1, v1 row_half_mirror row_mask:0xf bank_mask:0xf bound_ctrl:1
	v_add_f32_dpp v26, v26, v26 row_ror:4 row_mask:0xf bank_mask:0xf bound_ctrl:1
	s_nop 0
	v_add_f32_dpp v0, v0, v0 row_mirror row_mask:0xf bank_mask:0xf bound_ctrl:1
	v_add_f32_dpp v1, v1, v1 row_mirror row_mask:0xf bank_mask:0xf bound_ctrl:1
	v_add_f32_dpp v26, v26, v26 row_ror:8 row_mask:0xf bank_mask:0xf bound_ctrl:1
	ds_write_b32 v76, v26 offset:128
	v_pk_fma_f32 v[8:9], v[40:41], v[0:1], v[12:13] op_sel_hi:[0,1,1]
	v_pk_fma_f32 v[10:11], v[40:41], v[0:1], v[14:15] op_sel:[1,0,0]
	v_pk_fma_f32 v[20:21], v[42:43], v[0:1], v[16:17] op_sel_hi:[0,1,1]
	v_pk_fma_f32 v[22:23], v[42:43], v[0:1], v[18:19] op_sel:[1,0,0]
	v_pk_mul_f32 v[4:5], v[8:9], v[44:45] op_sel_hi:[1,0]
	v_pk_mul_f32 v[6:7], v[10:11], v[44:45] op_sel:[0,1]
	v_pk_fma_f32 v[4:5], v[20:21], v[46:47], v[4:5] op_sel_hi:[1,0,1]
	v_pk_fma_f32 v[6:7], v[22:23], v[46:47], v[6:7] op_sel:[0,1,0]
	ds_read_b128 v[28:31], v74 offset:25600
	ds_read_b128 v[32:35], v74 offset:9216
	ds_read_b128 v[36:39], v74 offset:17408
	ds_read_b128 v[40:43], v74 offset:33792
	ds_read_b128 v[44:47], v74 offset:1024
	ds_read_b64 v[48:49], v75 offset:41472
	s_waitcnt lgkmcnt(7)
	v_pk_mul_f32 v[0:1], v[8:9], v[106:107] op_sel_hi:[1,0]
	v_pk_mul_f32 v[2:3], v[10:11], v[106:107] op_sel:[0,1]
	v_pk_fma_f32 v[0:1], v[20:21], v[108:109], v[0:1] op_sel_hi:[1,0,1]
	v_pk_fma_f32 v[2:3], v[22:23], v[108:109], v[2:3] op_sel:[0,1,0]
	v_pk_add_f32 v[4:5], v[4:5], v[6:7]
	v_pk_mul_f32 v[12:13], v[8:9], v[110:111] op_sel_hi:[1,0]
	v_pk_add_f32 v[0:1], v[0:1], v[2:3]
	v_pk_mul_f32 v[14:15], v[10:11], v[110:111] op_sel:[0,1]
	v_cndmask_b32_e32 v24, v4, v5, vcc
	v_cndmask_b32_e32 v25, v5, v4, vcc
	v_pk_mul_f32 v[16:17], v[20:21], v[112:113] op_sel_hi:[1,0]
	v_pk_mul_f32 v[18:19], v[22:23], v[112:113] op_sel:[0,1]
	v_add_f32_dpp v0, v0, v0 quad_perm:[1,0,3,2] row_mask:0xf bank_mask:0xf bound_ctrl:1
	v_add_f32_dpp v1, v1, v1 quad_perm:[1,0,3,2] row_mask:0xf bank_mask:0xf bound_ctrl:1
	v_add_f32_dpp v26, v25, v24 quad_perm:[1,0,3,2] row_mask:0xf bank_mask:0xf bound_ctrl:1
	v_pk_fma_f32 v[12:13], v[114:115], v[126:127], v[12:13] op_sel_hi:[0,1,1]
	v_pk_fma_f32 v[14:15], v[114:115], v[126:127], v[14:15] op_sel:[1,0,0]
	v_add_f32_dpp v0, v0, v0 quad_perm:[2,3,0,1] row_mask:0xf bank_mask:0xf bound_ctrl:1
	v_add_f32_dpp v1, v1, v1 quad_perm:[2,3,0,1] row_mask:0xf bank_mask:0xf bound_ctrl:1
	v_add_f32_dpp v26, v26, v26 quad_perm:[2,3,0,1] row_mask:0xf bank_mask:0xf bound_ctrl:1
	v_pk_fma_f32 v[16:17], v[116:117], v[126:127], v[16:17] op_sel_hi:[0,1,1]
	v_pk_fma_f32 v[18:19], v[116:117], v[126:127], v[18:19] op_sel:[1,0,0]
	v_add_f32_dpp v0, v0, v0 row_half_mirror row_mask:0xf bank_mask:0xf bound_ctrl:1
	v_add_f32_dpp v1, v1, v1 row_half_mirror row_mask:0xf bank_mask:0xf bound_ctrl:1
	v_add_f32_dpp v26, v26, v26 row_ror:4 row_mask:0xf bank_mask:0xf bound_ctrl:1
	s_nop 0
	v_add_f32_dpp v0, v0, v0 row_mirror row_mask:0xf bank_mask:0xf bound_ctrl:1
	v_add_f32_dpp v1, v1, v1 row_mirror row_mask:0xf bank_mask:0xf bound_ctrl:1
	v_add_f32_dpp v26, v26, v26 row_ror:8 row_mask:0xf bank_mask:0xf bound_ctrl:1
	ds_write_b32 v76, v26 offset:256
	v_pk_fma_f32 v[8:9], v[118:119], v[0:1], v[12:13] op_sel_hi:[0,1,1]
	v_pk_fma_f32 v[10:11], v[118:119], v[0:1], v[14:15] op_sel:[1,0,0]
	v_pk_fma_f32 v[20:21], v[120:121], v[0:1], v[16:17] op_sel_hi:[0,1,1]
	v_pk_fma_f32 v[22:23], v[120:121], v[0:1], v[18:19] op_sel:[1,0,0]
	v_pk_mul_f32 v[4:5], v[8:9], v[122:123] op_sel_hi:[1,0]
	v_pk_mul_f32 v[6:7], v[10:11], v[122:123] op_sel:[0,1]
	v_pk_fma_f32 v[4:5], v[20:21], v[124:125], v[4:5] op_sel_hi:[1,0,1]
	v_pk_fma_f32 v[6:7], v[22:23], v[124:125], v[6:7] op_sel:[0,1,0]
	ds_read_b128 v[106:109], v74 offset:25856
	ds_read_b128 v[110:113], v74 offset:9472
	ds_read_b128 v[114:117], v74 offset:17664
	ds_read_b128 v[118:121], v74 offset:34048
	ds_read_b128 v[122:125], v74 offset:1280
	ds_read_b64 v[126:127], v75 offset:41600
	s_waitcnt lgkmcnt(7)
; __device__ __forceinline__ void rwkv_scan_phase(Frame& F, const bf16* RKV, const float* WAG, const bf16* AGB, const float* k_k, const float* k_a, const float* r_k, bf16* Y, float* BS, float* ST2) {
;     ...
;                 f32x2 r0[4], w0[4], k0[4], a0[4], b0[4], r1[4], w1[4], k1[4], a1[4], b1[4]; float v0, v1;
;                 SC_LOAD(r0, w0, k0, a0, b0, v0, 0);
; #pragma unroll
;                 for (int t = 0; t < SC_T; t += 2) {
;                     SC_LOAD(r1, w1, k1, a1, b1, v1, t + 1);
;                     SC_STEP(r0, w0, k0, a0, b0, v0, t);
;                     if (t + 2 < SC_T) SC_LOAD(r0, w0, k0, a0, b0, v0, t + 2);
;                     SC_STEP(r1, w1, k1, a1, b1, v1, t + 1);
;                 }
	v_pk_mul_f32 v[0:1], v[8:9], v[28:29] op_sel_hi:[1,0]
	v_pk_mul_f32 v[2:3], v[10:11], v[28:29] op_sel:[0,1]
	v_pk_fma_f32 v[0:1], v[20:21], v[30:31], v[0:1] op_sel_hi:[1,0,1]
	v_pk_fma_f32 v[2:3], v[22:23], v[30:31], v[2:3] op_sel:[0,1,0]
	v_pk_add_f32 v[4:5], v[4:5], v[6:7]
	v_pk_mul_f32 v[12:13], v[8:9], v[32:33] op_sel_hi:[1,0]
	v_pk_add_f32 v[0:1], v[0:1], v[2:3]
	v_pk_mul_f32 v[14:15], v[10:11], v[32:33] op_sel:[0,1]
	v_cndmask_b32_e32 v24, v4, v5, vcc
	v_cndmask_b32_e32 v25, v5, v4, vcc
	v_pk_mul_f32 v[16:17], v[20:21], v[34:35] op_sel_hi:[1,0]
	v_pk_mul_f32 v[18:19], v[22:23], v[34:35] op_sel:[0,1]
	v_add_f32_dpp v0, v0, v0 quad_perm:[1,0,3,2] row_mask:0xf bank_mask:0xf bound_ctrl:1
	v_add_f32_dpp v1, v1, v1 quad_perm:[1,0,3,2] row_mask:0xf bank_mask:0xf bound_ctrl:1
	v_add_f32_dpp v26, v25, v24 quad_perm:[1,0,3,2] row_mask:0xf bank_mask:0xf bound_ctrl:1
	v_pk_fma_f32 v[12:13], v[36:37], v[48:49], v[12:13] op_sel_hi:[0,1,1]
	v_pk_fma_f32 v[14:15], v[36:37], v[48:49], v[14:15] op_sel:[1,0,0]
	v_add_f32_dpp v0, v0, v0 quad_perm:[2,3,0,1] row_mask:0xf bank_mask:0xf bound_ctrl:1
	v_add_f32_dpp v1, v1, v1 quad_perm:[2,3,0,1] row_mask:0xf bank_mask:0xf bound_ctrl:1
	v_add_f32_dpp v26, v26, v26 quad_perm:[2,3,0,1] row_mask:0xf bank_mask:0xf bound_ctrl:1
	v_pk_fma_f32 v[16:17], v[38:39], v[48:49], v[16:17] op_sel_hi:[0,1,1]
	v_pk_fma_f32 v[18:19], v[38:39], v[48:49], v[18:19] op_sel:[1,0,0]
	v_add_f32_dpp v0, v0, v0 row_half_mirror row_mask:0xf bank_mask:0xf bound_ctrl:1
	v_add_f32_dpp v1, v1, v1 row_half_mirror row_mask:0xf bank_mask:0xf bound_ctrl:1
	v_add_f32_dpp v26, v26, v26 row_ror:4 row_mask:0xf bank_mask:0xf bound_ctrl:1
	s_nop 0
	v_add_f32_dpp v0, v0, v0 row_mirror row_mask:0xf bank_mask:0xf bound_ctrl:1
	v_add_f32_dpp v1, v1, v1 row_mirror row_mask:0xf bank_mask:0xf bound_ctrl:1
	v_add_f32_dpp v26, v26, v26 row_ror:8 row_mask:0xf bank_mask:0xf bound_ctrl:1
	ds_write_b32 v76, v26 offset:384
	v_pk_fma_f32 v[8:9], v[40:41], v[0:1], v[12:13] op_sel_hi:[0,1,1]
	v_pk_fma_f32 v[10:11], v[40:41], v[0:1], v[14:15] op_sel:[1,0,0]
	v_pk_fma_f32 v[20:21], v[42:43], v[0:1], v[16:17] op_sel_hi:[0,1,1]
	v_pk_fma_f32 v[22:23], v[42:43], v[0:1], v[18:19] op_sel:[1,0,0]
	v_pk_mul_f32 v[4:5], v[8:9], v[44:45] op_sel_hi:[1,0]
	v_pk_mul_f32 v[6:7], v[10:11], v[44:45] op_sel:[0,1]
	v_pk_fma_f32 v[4:5], v[20:21], v[46:47], v[4:5] op_sel_hi:[1,0,1]
	v_pk_fma_f32 v[6:7], v[22:23], v[46:47], v[6:7] op_sel:[0,1,0]
	ds_read_b128 v[28:31], v74 offset:26112
	ds_read_b128 v[32:35], v74 offset:9728
	ds_read_b128 v[36:39], v74 offset:17920
	ds_read_b128 v[40:43], v74 offset:34304
	ds_read_b128 v[44:47], v74 offset:1536
	ds_read_b64 v[48:49], v75 offset:41728
	s_waitcnt lgkmcnt(7)
	v_pk_mul_f32 v[0:1], v[8:9], v[106:107] op_sel_hi:[1,0]
	v_pk_mul_f32 v[2:3], v[10:11], v[106:107] op_sel:[0,1]
	v_pk_fma_f32 v[0:1], v[20:21], v[108:109], v[0:1] op_sel_hi:[1,0,1]
	v_pk_fma_f32 v[2:3], v[22:23], v[108:109], v[2:3] op_sel:[0,1,0]
	v_pk_add_f32 v[4:5], v[4:5], v[6:7]
	v_pk_mul_f32 v[12:13], v[8:9], v[110:111] op_sel_hi:[1,0]
	v_pk_add_f32 v[0:1], v[0:1], v[2:3]
	v_pk_mul_f32 v[14:15], v[10:11], v[110:111] op_sel:[0,1]
	v_cndmask_b32_e32 v24, v4, v5, vcc
	v_cndmask_b32_e32 v25, v5, v4, vcc
	v_pk_mul_f32 v[16:17], v[20:21], v[112:113] op_sel_hi:[1,0]
	v_pk_mul_f32 v[18:19], v[22:23], v[112:113] op_sel:[0,1]
	v_add_f32_dpp v0, v0, v0 quad_perm:[1,0,3,2] row_mask:0xf bank_mask:0xf bound_ctrl:1
	v_add_f32_dpp v1, v1, v1 quad_perm:[1,0,3,2] row_mask:0xf bank_mask:0xf bound_ctrl:1
	v_add_f32_dpp v26, v25, v24 quad_perm:[1,0,3,2] row_mask:0xf bank_mask:0xf bound_ctrl:1
	v_pk_fma_f32 v[12:13], v[114:115], v[126:127], v[12:13] op_sel_hi:[0,1,1]
	v_pk_fma_f32 v[14:15], v[114:115], v[126:127], v[14:15] op_sel:[1,0,0]
	v_add_f32_dpp v0, v0, v0 quad_perm:[2,3,0,1] row_mask:0xf bank_mask:0xf bound_ctrl:1
	v_add_f32_dpp v1, v1, v1 quad_perm:[2,3,0,1] row_mask:0xf bank_mask:0xf bound_ctrl:1
	v_add_f32_dpp v26, v26, v26 quad_perm:[2,3,0,1] row_mask:0xf bank_mask:0xf bound_ctrl:1
	v_pk_fma_f32 v[16:17], v[116:117], v[126:127], v[16:17] op_sel_hi:[0,1,1]
	v_pk_fma_f32 v[18:19], v[116:117], v[126:127], v[18:19] op_sel:[1,0,0]
	v_add_f32_dpp v0, v0, v0 row_half_mirror row_mask:0xf bank_mask:0xf bound_ctrl:1
	v_add_f32_dpp v1, v1, v1 row_half_mirror row_mask:0xf bank_mask:0xf bound_ctrl:1
	v_add_f32_dpp v26, v26, v26 row_ror:4 row_mask:0xf bank_mask:0xf bound_ctrl:1
	s_nop 0
	v_add_f32_dpp v0, v0, v0 row_mirror row_mask:0xf bank_mask:0xf bound_ctrl:1
	v_add_f32_dpp v1, v1, v1 row_mirror row_mask:0xf bank_mask:0xf bound_ctrl:1
	v_add_f32_dpp v26, v26, v26 row_ror:8 row_mask:0xf bank_mask:0xf bound_ctrl:1
	ds_write_b32 v76, v26 offset:512
	v_pk_fma_f32 v[8:9], v[118:119], v[0:1], v[12:13] op_sel_hi:[0,1,1]
	v_pk_fma_f32 v[10:11], v[118:119], v[0:1], v[14:15] op_sel:[1,0,0]
	v_pk_fma_f32 v[20:21], v[120:121], v[0:1], v[16:17] op_sel_hi:[0,1,1]
	v_pk_fma_f32 v[22:23], v[120:121], v[0:1], v[18:19] op_sel:[1,0,0]
	v_pk_mul_f32 v[4:5], v[8:9], v[122:123] op_sel_hi:[1,0]
	v_pk_mul_f32 v[6:7], v[10:11], v[122:123] op_sel:[0,1]
	v_pk_fma_f32 v[4:5], v[20:21], v[124:125], v[4:5] op_sel_hi:[1,0,1]
	v_pk_fma_f32 v[6:7], v[22:23], v[124:125], v[6:7] op_sel:[0,1,0]
	ds_read_b128 v[106:109], v74 offset:26368
	ds_read_b128 v[110:113], v74 offset:9984
	ds_read_b128 v[114:117], v74 offset:18176
	ds_read_b128 v[118:121], v74 offset:34560
	ds_read_b128 v[122:125], v74 offset:1792
	ds_read_b64 v[126:127], v75 offset:41856
	s_waitcnt lgkmcnt(7)
; __device__ __forceinline__ void rwkv_scan_phase(Frame& F, const bf16* RKV, const float* WAG, const bf16* AGB, const float* k_k, const float* k_a, const float* r_k, bf16* Y, float* BS, float* ST2) {
;     ...
;                 f32x2 r0[4], w0[4], k0[4], a0[4], b0[4], r1[4], w1[4], k1[4], a1[4], b1[4]; float v0, v1;
;                 SC_LOAD(r0, w0, k0, a0, b0, v0, 0);
; #pragma unroll
;                 for (int t = 0; t < SC_T; t += 2) {
;                     SC_LOAD(r1, w1, k1, a1, b1, v1, t + 1);
;                     SC_STEP(r0, w0, k0, a0, b0, v0, t);
;                     if (t + 2 < SC_T) SC_LOAD(r0, w0, k0, a0, b0, v0, t + 2);
;                     SC_STEP(r1, w1, k1, a1, b1, v1, t + 1);
;                 }
	v_pk_mul_f32 v[0:1], v[8:9], v[28:29] op_sel_hi:[1,0]
	v_pk_mul_f32 v[2:3], v[10:11], v[28:29] op_sel:[0,1]
	v_pk_fma_f32 v[0:1], v[20:21], v[30:31], v[0:1] op_sel_hi:[1,0,1]
	v_pk_fma_f32 v[2:3], v[22:23], v[30:31], v[2:3] op_sel:[0,1,0]
	v_pk_add_f32 v[4:5], v[4:5], v[6:7]
	v_pk_mul_f32 v[12:13], v[8:9], v[32:33] op_sel_hi:[1,0]
	v_pk_add_f32 v[0:1], v[0:1], v[2:3]
	v_pk_mul_f32 v[14:15], v[10:11], v[32:33] op_sel:[0,1]
	v_cndmask_b32_e32 v24, v4, v5, vcc
	v_cndmask_b32_e32 v25, v5, v4, vcc
	v_pk_mul_f32 v[16:17], v[20:21], v[34:35] op_sel_hi:[1,0]
	v_pk_mul_f32 v[18:19], v[22:23], v[34:35] op_sel:[0,1]
	v_add_f32_dpp v0, v0, v0 quad_perm:[1,0,3,2] row_mask:0xf bank_mask:0xf bound_ctrl:1
	v_add_f32_dpp v1, v1, v1 quad_perm:[1,0,3,2] row_mask:0xf bank_mask:0xf bound_ctrl:1
	v_add_f32_dpp v26, v25, v24 quad_perm:[1,0,3,2] row_mask:0xf bank_mask:0xf bound_ctrl:1
	v_pk_fma_f32 v[12:13], v[36:37], v[48:49], v[12:13] op_sel_hi:[0,1,1]
	v_pk_fma_f32 v[14:15], v[36:37], v[48:49], v[14:15] op_sel:[1,0,0]
	v_add_f32_dpp v0, v0, v0 quad_perm:[2,3,0,1] row_mask:0xf bank_mask:0xf bound_ctrl:1
	v_add_f32_dpp v1, v1, v1 quad_perm:[2,3,0,1] row_mask:0xf bank_mask:0xf bound_ctrl:1
	v_add_f32_dpp v26, v26, v26 quad_perm:[2,3,0,1] row_mask:0xf bank_mask:0xf bound_ctrl:1
	v_pk_fma_f32 v[16:17], v[38:39], v[48:49], v[16:17] op_sel_hi:[0,1,1]
	v_pk_fma_f32 v[18:19], v[38:39], v[48:49], v[18:19] op_sel:[1,0,0]
	v_add_f32_dpp v0, v0, v0 row_half_mirror row_mask:0xf bank_mask:0xf bound_ctrl:1
	v_add_f32_dpp v1, v1, v1 row_half_mirror row_mask:0xf bank_mask:0xf bound_ctrl:1
	v_add_f32_dpp v26, v26, v26 row_ror:4 row_mask:0xf bank_mask:0xf bound_ctrl:1
	s_nop 0
	v_add_f32_dpp v0, v0, v0 row_mirror row_mask:0xf bank_mask:0xf bound_ctrl:1
	v_add_f32_dpp v1, v1, v1 row_mirror row_mask:0xf bank_mask:0xf bound_ctrl:1
	v_add_f32_dpp v26, v26, v26 row_ror:8 row_mask:0xf bank_mask:0xf bound_ctrl:1
	ds_write_b32 v76, v26 offset:640
	v_pk_fma_f32 v[8:9], v[40:41], v[0:1], v[12:13] op_sel_hi:[0,1,1]
	v_pk_fma_f32 v[10:11], v[40:41], v[0:1], v[14:15] op_sel:[1,0,0]
	v_pk_fma_f32 v[20:21], v[42:43], v[0:1], v[16:17] op_sel_hi:[0,1,1]
	v_pk_fma_f32 v[22:23], v[42:43], v[0:1], v[18:19] op_sel:[1,0,0]
	v_pk_mul_f32 v[4:5], v[8:9], v[44:45] op_sel_hi:[1,0]
	v_pk_mul_f32 v[6:7], v[10:11], v[44:45] op_sel:[0,1]
	v_pk_fma_f32 v[4:5], v[20:21], v[46:47], v[4:5] op_sel_hi:[1,0,1]
	v_pk_fma_f32 v[6:7], v[22:23], v[46:47], v[6:7] op_sel:[0,1,0]
	ds_read_b128 v[28:31], v74 offset:26624
	ds_read_b128 v[32:35], v74 offset:10240
	ds_read_b128 v[36:39], v74 offset:18432
	ds_read_b128 v[40:43], v74 offset:34816
	ds_read_b128 v[44:47], v74 offset:2048
	ds_read_b64 v[48:49], v75 offset:41984
	s_waitcnt lgkmcnt(7)
	v_pk_mul_f32 v[0:1], v[8:9], v[106:107] op_sel_hi:[1,0]
	v_pk_mul_f32 v[2:3], v[10:11], v[106:107] op_sel:[0,1]
	v_pk_fma_f32 v[0:1], v[20:21], v[108:109], v[0:1] op_sel_hi:[1,0,1]
	v_pk_fma_f32 v[2:3], v[22:23], v[108:109], v[2:3] op_sel:[0,1,0]
	v_pk_add_f32 v[4:5], v[4:5], v[6:7]
	v_pk_mul_f32 v[12:13], v[8:9], v[110:111] op_sel_hi:[1,0]
	v_pk_add_f32 v[0:1], v[0:1], v[2:3]
	v_pk_mul_f32 v[14:15], v[10:11], v[110:111] op_sel:[0,1]
	v_cndmask_b32_e32 v24, v4, v5, vcc
	v_cndmask_b32_e32 v25, v5, v4, vcc
	v_pk_mul_f32 v[16:17], v[20:21], v[112:113] op_sel_hi:[1,0]
	v_pk_mul_f32 v[18:19], v[22:23], v[112:113] op_sel:[0,1]
	v_add_f32_dpp v0, v0, v0 quad_perm:[1,0,3,2] row_mask:0xf bank_mask:0xf bound_ctrl:1
	v_add_f32_dpp v1, v1, v1 quad_perm:[1,0,3,2] row_mask:0xf bank_mask:0xf bound_ctrl:1
	v_add_f32_dpp v26, v25, v24 quad_perm:[1,0,3,2] row_mask:0xf bank_mask:0xf bound_ctrl:1
	v_pk_fma_f32 v[12:13], v[114:115], v[126:127], v[12:13] op_sel_hi:[0,1,1]
	v_pk_fma_f32 v[14:15], v[114:115], v[126:127], v[14:15] op_sel:[1,0,0]
	v_add_f32_dpp v0, v0, v0 quad_perm:[2,3,0,1] row_mask:0xf bank_mask:0xf bound_ctrl:1
	v_add_f32_dpp v1, v1, v1 quad_perm:[2,3,0,1] row_mask:0xf bank_mask:0xf bound_ctrl:1
	v_add_f32_dpp v26, v26, v26 quad_perm:[2,3,0,1] row_mask:0xf bank_mask:0xf bound_ctrl:1
	v_pk_fma_f32 v[16:17], v[116:117], v[126:127], v[16:17] op_sel_hi:[0,1,1]
	v_pk_fma_f32 v[18:19], v[116:117], v[126:127], v[18:19] op_sel:[1,0,0]
	v_add_f32_dpp v0, v0, v0 row_half_mirror row_mask:0xf bank_mask:0xf bound_ctrl:1
	v_add_f32_dpp v1, v1, v1 row_half_mirror row_mask:0xf bank_mask:0xf bound_ctrl:1
	v_add_f32_dpp v26, v26, v26 row_ror:4 row_mask:0xf bank_mask:0xf bound_ctrl:1
	s_nop 0
	v_add_f32_dpp v0, v0, v0 row_mirror row_mask:0xf bank_mask:0xf bound_ctrl:1
	v_add_f32_dpp v1, v1, v1 row_mirror row_mask:0xf bank_mask:0xf bound_ctrl:1
	v_add_f32_dpp v26, v26, v26 row_ror:8 row_mask:0xf bank_mask:0xf bound_ctrl:1
	ds_write_b32 v76, v26 offset:768
	v_pk_fma_f32 v[8:9], v[118:119], v[0:1], v[12:13] op_sel_hi:[0,1,1]
	v_pk_fma_f32 v[10:11], v[118:119], v[0:1], v[14:15] op_sel:[1,0,0]
	v_pk_fma_f32 v[20:21], v[120:121], v[0:1], v[16:17] op_sel_hi:[0,1,1]
	v_pk_fma_f32 v[22:23], v[120:121], v[0:1], v[18:19] op_sel:[1,0,0]
	v_pk_mul_f32 v[4:5], v[8:9], v[122:123] op_sel_hi:[1,0]
	v_pk_mul_f32 v[6:7], v[10:11], v[122:123] op_sel:[0,1]
	v_pk_fma_f32 v[4:5], v[20:21], v[124:125], v[4:5] op_sel_hi:[1,0,1]
	v_pk_fma_f32 v[6:7], v[22:23], v[124:125], v[6:7] op_sel:[0,1,0]
	ds_read_b128 v[106:109], v74 offset:26880
	ds_read_b128 v[110:113], v74 offset:10496
	ds_read_b128 v[114:117], v74 offset:18688
	ds_read_b128 v[118:121], v74 offset:35072
	ds_read_b128 v[122:125], v74 offset:2304
	ds_read_b64 v[126:127], v75 offset:42112
	s_waitcnt lgkmcnt(7)
; __device__ __forceinline__ void rwkv_scan_phase(Frame& F, const bf16* RKV, const float* WAG, const bf16* AGB, const float* k_k, const float* k_a, const float* r_k, bf16* Y, float* BS, float* ST2) {
;     ...
;                 f32x2 r0[4], w0[4], k0[4], a0[4], b0[4], r1[4], w1[4], k1[4], a1[4], b1[4]; float v0, v1;
;                 SC_LOAD(r0, w0, k0, a0, b0, v0, 0);
; #pragma unroll
;                 for (int t = 0; t < SC_T; t += 2) {
;                     SC_LOAD(r1, w1, k1, a1, b1, v1, t + 1);
;                     SC_STEP(r0, w0, k0, a0, b0, v0, t);
;                     if (t + 2 < SC_T) SC_LOAD(r0, w0, k0, a0, b0, v0, t + 2);
;                     SC_STEP(r1, w1, k1, a1, b1, v1, t + 1);
;                 }
	v_pk_mul_f32 v[0:1], v[8:9], v[28:29] op_sel_hi:[1,0]
	v_pk_mul_f32 v[2:3], v[10:11], v[28:29] op_sel:[0,1]
	v_pk_fma_f32 v[0:1], v[20:21], v[30:31], v[0:1] op_sel_hi:[1,0,1]
	v_pk_fma_f32 v[2:3], v[22:23], v[30:31], v[2:3] op_sel:[0,1,0]
	v_pk_add_f32 v[4:5], v[4:5], v[6:7]
	v_pk_mul_f32 v[12:13], v[8:9], v[32:33] op_sel_hi:[1,0]
	v_pk_add_f32 v[0:1], v[0:1], v[2:3]
	v_pk_mul_f32 v[14:15], v[10:11], v[32:33] op_sel:[0,1]
	v_cndmask_b32_e32 v24, v4, v5, vcc
	v_cndmask_b32_e32 v25, v5, v4, vcc
	v_pk_mul_f32 v[16:17], v[20:21], v[34:35] op_sel_hi:[1,0]
	v_pk_mul_f32 v[18:19], v[22:23], v[34:35] op_sel:[0,1]
	v_add_f32_dpp v0, v0, v0 quad_perm:[1,0,3,2] row_mask:0xf bank_mask:0xf bound_ctrl:1
	v_add_f32_dpp v1, v1, v1 quad_perm:[1,0,3,2] row_mask:0xf bank_mask:0xf bound_ctrl:1
	v_add_f32_dpp v26, v25, v24 quad_perm:[1,0,3,2] row_mask:0xf bank_mask:0xf bound_ctrl:1
	v_pk_fma_f32 v[12:13], v[36:37], v[48:49], v[12:13] op_sel_hi:[0,1,1]
	v_pk_fma_f32 v[14:15], v[36:37], v[48:49], v[14:15] op_sel:[1,0,0]
	v_add_f32_dpp v0, v0, v0 quad_perm:[2,3,0,1] row_mask:0xf bank_mask:0xf bound_ctrl:1
	v_add_f32_dpp v1, v1, v1 quad_perm:[2,3,0,1] row_mask:0xf bank_mask:0xf bound_ctrl:1
	v_add_f32_dpp v26, v26, v26 quad_perm:[2,3,0,1] row_mask:0xf bank_mask:0xf bound_ctrl:1
	v_pk_fma_f32 v[16:17], v[38:39], v[48:49], v[16:17] op_sel_hi:[0,1,1]
	v_pk_fma_f32 v[18:19], v[38:39], v[48:49], v[18:19] op_sel:[1,0,0]
	v_add_f32_dpp v0, v0, v0 row_half_mirror row_mask:0xf bank_mask:0xf bound_ctrl:1
	v_add_f32_dpp v1, v1, v1 row_half_mirror row_mask:0xf bank_mask:0xf bound_ctrl:1
	v_add_f32_dpp v26, v26, v26 row_ror:4 row_mask:0xf bank_mask:0xf bound_ctrl:1
	s_nop 0
	v_add_f32_dpp v0, v0, v0 row_mirror row_mask:0xf bank_mask:0xf bound_ctrl:1
	v_add_f32_dpp v1, v1, v1 row_mirror row_mask:0xf bank_mask:0xf bound_ctrl:1
	v_add_f32_dpp v26, v26, v26 row_ror:8 row_mask:0xf bank_mask:0xf bound_ctrl:1
	ds_write_b32 v76, v26 offset:896
	v_pk_fma_f32 v[8:9], v[40:41], v[0:1], v[12:13] op_sel_hi:[0,1,1]
	v_pk_fma_f32 v[10:11], v[40:41], v[0:1], v[14:15] op_sel:[1,0,0]
	v_pk_fma_f32 v[20:21], v[42:43], v[0:1], v[16:17] op_sel_hi:[0,1,1]
	v_pk_fma_f32 v[22:23], v[42:43], v[0:1], v[18:19] op_sel:[1,0,0]
	v_pk_mul_f32 v[4:5], v[8:9], v[44:45] op_sel_hi:[1,0]
	v_pk_mul_f32 v[6:7], v[10:11], v[44:45] op_sel:[0,1]
	v_pk_fma_f32 v[4:5], v[20:21], v[46:47], v[4:5] op_sel_hi:[1,0,1]
	v_pk_fma_f32 v[6:7], v[22:23], v[46:47], v[6:7] op_sel:[0,1,0]
	ds_read_b128 v[28:31], v74 offset:27136
	ds_read_b128 v[32:35], v74 offset:10752
	ds_read_b128 v[36:39], v74 offset:18944
	ds_read_b128 v[40:43], v74 offset:35328
	ds_read_b128 v[44:47], v74 offset:2560
	ds_read_b64 v[48:49], v75 offset:42240
	s_waitcnt lgkmcnt(7)
	v_pk_mul_f32 v[0:1], v[8:9], v[106:107] op_sel_hi:[1,0]
	v_pk_mul_f32 v[2:3], v[10:11], v[106:107] op_sel:[0,1]
	v_pk_fma_f32 v[0:1], v[20:21], v[108:109], v[0:1] op_sel_hi:[1,0,1]
	v_pk_fma_f32 v[2:3], v[22:23], v[108:109], v[2:3] op_sel:[0,1,0]
	v_pk_add_f32 v[4:5], v[4:5], v[6:7]
	v_pk_mul_f32 v[12:13], v[8:9], v[110:111] op_sel_hi:[1,0]
	v_pk_add_f32 v[0:1], v[0:1], v[2:3]
	v_pk_mul_f32 v[14:15], v[10:11], v[110:111] op_sel:[0,1]
	v_cndmask_b32_e32 v24, v4, v5, vcc
	v_cndmask_b32_e32 v25, v5, v4, vcc
	v_pk_mul_f32 v[16:17], v[20:21], v[112:113] op_sel_hi:[1,0]
	v_pk_mul_f32 v[18:19], v[22:23], v[112:113] op_sel:[0,1]
	v_add_f32_dpp v0, v0, v0 quad_perm:[1,0,3,2] row_mask:0xf bank_mask:0xf bound_ctrl:1
	v_add_f32_dpp v1, v1, v1 quad_perm:[1,0,3,2] row_mask:0xf bank_mask:0xf bound_ctrl:1
	v_add_f32_dpp v26, v25, v24 quad_perm:[1,0,3,2] row_mask:0xf bank_mask:0xf bound_ctrl:1
	v_pk_fma_f32 v[12:13], v[114:115], v[126:127], v[12:13] op_sel_hi:[0,1,1]
	v_pk_fma_f32 v[14:15], v[114:115], v[126:127], v[14:15] op_sel:[1,0,0]
	v_add_f32_dpp v0, v0, v0 quad_perm:[2,3,0,1] row_mask:0xf bank_mask:0xf bound_ctrl:1
	v_add_f32_dpp v1, v1, v1 quad_perm:[2,3,0,1] row_mask:0xf bank_mask:0xf bound_ctrl:1
	v_add_f32_dpp v26, v26, v26 quad_perm:[2,3,0,1] row_mask:0xf bank_mask:0xf bound_ctrl:1
	v_pk_fma_f32 v[16:17], v[116:117], v[126:127], v[16:17] op_sel_hi:[0,1,1]
	v_pk_fma_f32 v[18:19], v[116:117], v[126:127], v[18:19] op_sel:[1,0,0]
	v_add_f32_dpp v0, v0, v0 row_half_mirror row_mask:0xf bank_mask:0xf bound_ctrl:1
	v_add_f32_dpp v1, v1, v1 row_half_mirror row_mask:0xf bank_mask:0xf bound_ctrl:1
	v_add_f32_dpp v26, v26, v26 row_ror:4 row_mask:0xf bank_mask:0xf bound_ctrl:1
	s_nop 0
	v_add_f32_dpp v0, v0, v0 row_mirror row_mask:0xf bank_mask:0xf bound_ctrl:1
	v_add_f32_dpp v1, v1, v1 row_mirror row_mask:0xf bank_mask:0xf bound_ctrl:1
	v_add_f32_dpp v26, v26, v26 row_ror:8 row_mask:0xf bank_mask:0xf bound_ctrl:1
	ds_write_b32 v76, v26 offset:1024
	v_pk_fma_f32 v[8:9], v[118:119], v[0:1], v[12:13] op_sel_hi:[0,1,1]
	v_pk_fma_f32 v[10:11], v[118:119], v[0:1], v[14:15] op_sel:[1,0,0]
	v_pk_fma_f32 v[20:21], v[120:121], v[0:1], v[16:17] op_sel_hi:[0,1,1]
	v_pk_fma_f32 v[22:23], v[120:121], v[0:1], v[18:19] op_sel:[1,0,0]
	v_pk_mul_f32 v[4:5], v[8:9], v[122:123] op_sel_hi:[1,0]
	v_pk_mul_f32 v[6:7], v[10:11], v[122:123] op_sel:[0,1]
	v_pk_fma_f32 v[4:5], v[20:21], v[124:125], v[4:5] op_sel_hi:[1,0,1]
	v_pk_fma_f32 v[6:7], v[22:23], v[124:125], v[6:7] op_sel:[0,1,0]
	ds_read_b128 v[106:109], v74 offset:27392
	ds_read_b128 v[110:113], v74 offset:11008
	ds_read_b128 v[114:117], v74 offset:19200
	ds_read_b128 v[118:121], v74 offset:35584
	ds_read_b128 v[122:125], v74 offset:2816
	ds_read_b64 v[126:127], v75 offset:42368
	s_waitcnt lgkmcnt(7)
; __device__ __forceinline__ void rwkv_scan_phase(Frame& F, const bf16* RKV, const float* WAG, const bf16* AGB, const float* k_k, const float* k_a, const float* r_k, bf16* Y, float* BS, float* ST2) {
;     ...
;                 f32x2 r0[4], w0[4], k0[4], a0[4], b0[4], r1[4], w1[4], k1[4], a1[4], b1[4]; float v0, v1;
;                 SC_LOAD(r0, w0, k0, a0, b0, v0, 0);
; #pragma unroll
;                 for (int t = 0; t < SC_T; t += 2) {
;                     SC_LOAD(r1, w1, k1, a1, b1, v1, t + 1);
;                     SC_STEP(r0, w0, k0, a0, b0, v0, t);
;                     if (t + 2 < SC_T) SC_LOAD(r0, w0, k0, a0, b0, v0, t + 2);
;                     SC_STEP(r1, w1, k1, a1, b1, v1, t + 1);
;                 }
	v_pk_mul_f32 v[0:1], v[8:9], v[28:29] op_sel_hi:[1,0]
	v_pk_mul_f32 v[2:3], v[10:11], v[28:29] op_sel:[0,1]
	v_pk_fma_f32 v[0:1], v[20:21], v[30:31], v[0:1] op_sel_hi:[1,0,1]
	v_pk_fma_f32 v[2:3], v[22:23], v[30:31], v[2:3] op_sel:[0,1,0]
	v_pk_add_f32 v[4:5], v[4:5], v[6:7]
	v_pk_mul_f32 v[12:13], v[8:9], v[32:33] op_sel_hi:[1,0]
	v_pk_add_f32 v[0:1], v[0:1], v[2:3]
	v_pk_mul_f32 v[14:15], v[10:11], v[32:33] op_sel:[0,1]
	v_cndmask_b32_e32 v24, v4, v5, vcc
	v_cndmask_b32_e32 v25, v5, v4, vcc
	v_pk_mul_f32 v[16:17], v[20:21], v[34:35] op_sel_hi:[1,0]
	v_pk_mul_f32 v[18:19], v[22:23], v[34:35] op_sel:[0,1]
	v_add_f32_dpp v0, v0, v0 quad_perm:[1,0,3,2] row_mask:0xf bank_mask:0xf bound_ctrl:1
	v_add_f32_dpp v1, v1, v1 quad_perm:[1,0,3,2] row_mask:0xf bank_mask:0xf bound_ctrl:1
	v_add_f32_dpp v26, v25, v24 quad_perm:[1,0,3,2] row_mask:0xf bank_mask:0xf bound_ctrl:1
	v_pk_fma_f32 v[12:13], v[36:37], v[48:49], v[12:13] op_sel_hi:[0,1,1]
	v_pk_fma_f32 v[14:15], v[36:37], v[48:49], v[14:15] op_sel:[1,0,0]
	v_add_f32_dpp v0, v0, v0 quad_perm:[2,3,0,1] row_mask:0xf bank_mask:0xf bound_ctrl:1
	v_add_f32_dpp v1, v1, v1 quad_perm:[2,3,0,1] row_mask:0xf bank_mask:0xf bound_ctrl:1
	v_add_f32_dpp v26, v26, v26 quad_perm:[2,3,0,1] row_mask:0xf bank_mask:0xf bound_ctrl:1
	v_pk_fma_f32 v[16:17], v[38:39], v[48:49], v[16:17] op_sel_hi:[0,1,1]
	v_pk_fma_f32 v[18:19], v[38:39], v[48:49], v[18:19] op_sel:[1,0,0]
	v_add_f32_dpp v0, v0, v0 row_half_mirror row_mask:0xf bank_mask:0xf bound_ctrl:1
	v_add_f32_dpp v1, v1, v1 row_half_mirror row_mask:0xf bank_mask:0xf bound_ctrl:1
	v_add_f32_dpp v26, v26, v26 row_ror:4 row_mask:0xf bank_mask:0xf bound_ctrl:1
	s_nop 0
	v_add_f32_dpp v0, v0, v0 row_mirror row_mask:0xf bank_mask:0xf bound_ctrl:1
	v_add_f32_dpp v1, v1, v1 row_mirror row_mask:0xf bank_mask:0xf bound_ctrl:1
	v_add_f32_dpp v26, v26, v26 row_ror:8 row_mask:0xf bank_mask:0xf bound_ctrl:1
	ds_write_b32 v76, v26 offset:1152
	v_pk_fma_f32 v[8:9], v[40:41], v[0:1], v[12:13] op_sel_hi:[0,1,1]
	v_pk_fma_f32 v[10:11], v[40:41], v[0:1], v[14:15] op_sel:[1,0,0]
	v_pk_fma_f32 v[20:21], v[42:43], v[0:1], v[16:17] op_sel_hi:[0,1,1]
	v_pk_fma_f32 v[22:23], v[42:43], v[0:1], v[18:19] op_sel:[1,0,0]
	v_pk_mul_f32 v[4:5], v[8:9], v[44:45] op_sel_hi:[1,0]
	v_pk_mul_f32 v[6:7], v[10:11], v[44:45] op_sel:[0,1]
	v_pk_fma_f32 v[4:5], v[20:21], v[46:47], v[4:5] op_sel_hi:[1,0,1]
	v_pk_fma_f32 v[6:7], v[22:23], v[46:47], v[6:7] op_sel:[0,1,0]
	ds_read_b128 v[28:31], v74 offset:27648
	ds_read_b128 v[32:35], v74 offset:11264
	ds_read_b128 v[36:39], v74 offset:19456
	ds_read_b128 v[40:43], v74 offset:35840
	ds_read_b128 v[44:47], v74 offset:3072
	ds_read_b64 v[48:49], v75 offset:42496
	s_waitcnt lgkmcnt(7)
	v_pk_mul_f32 v[0:1], v[8:9], v[106:107] op_sel_hi:[1,0]
	v_pk_mul_f32 v[2:3], v[10:11], v[106:107] op_sel:[0,1]
	v_pk_fma_f32 v[0:1], v[20:21], v[108:109], v[0:1] op_sel_hi:[1,0,1]
	v_pk_fma_f32 v[2:3], v[22:23], v[108:109], v[2:3] op_sel:[0,1,0]
	v_pk_add_f32 v[4:5], v[4:5], v[6:7]
	v_pk_mul_f32 v[12:13], v[8:9], v[110:111] op_sel_hi:[1,0]
	v_pk_add_f32 v[0:1], v[0:1], v[2:3]
	v_pk_mul_f32 v[14:15], v[10:11], v[110:111] op_sel:[0,1]
	v_cndmask_b32_e32 v24, v4, v5, vcc
	v_cndmask_b32_e32 v25, v5, v4, vcc
	v_pk_mul_f32 v[16:17], v[20:21], v[112:113] op_sel_hi:[1,0]
	v_pk_mul_f32 v[18:19], v[22:23], v[112:113] op_sel:[0,1]
	v_add_f32_dpp v0, v0, v0 quad_perm:[1,0,3,2] row_mask:0xf bank_mask:0xf bound_ctrl:1
	v_add_f32_dpp v1, v1, v1 quad_perm:[1,0,3,2] row_mask:0xf bank_mask:0xf bound_ctrl:1
	v_add_f32_dpp v26, v25, v24 quad_perm:[1,0,3,2] row_mask:0xf bank_mask:0xf bound_ctrl:1
	v_pk_fma_f32 v[12:13], v[114:115], v[126:127], v[12:13] op_sel_hi:[0,1,1]
	v_pk_fma_f32 v[14:15], v[114:115], v[126:127], v[14:15] op_sel:[1,0,0]
	v_add_f32_dpp v0, v0, v0 quad_perm:[2,3,0,1] row_mask:0xf bank_mask:0xf bound_ctrl:1
	v_add_f32_dpp v1, v1, v1 quad_perm:[2,3,0,1] row_mask:0xf bank_mask:0xf bound_ctrl:1
	v_add_f32_dpp v26, v26, v26 quad_perm:[2,3,0,1] row_mask:0xf bank_mask:0xf bound_ctrl:1
	v_pk_fma_f32 v[16:17], v[116:117], v[126:127], v[16:17] op_sel_hi:[0,1,1]
	v_pk_fma_f32 v[18:19], v[116:117], v[126:127], v[18:19] op_sel:[1,0,0]
	v_add_f32_dpp v0, v0, v0 row_half_mirror row_mask:0xf bank_mask:0xf bound_ctrl:1
	v_add_f32_dpp v1, v1, v1 row_half_mirror row_mask:0xf bank_mask:0xf bound_ctrl:1
	v_add_f32_dpp v26, v26, v26 row_ror:4 row_mask:0xf bank_mask:0xf bound_ctrl:1
	s_nop 0
	v_add_f32_dpp v0, v0, v0 row_mirror row_mask:0xf bank_mask:0xf bound_ctrl:1
	v_add_f32_dpp v1, v1, v1 row_mirror row_mask:0xf bank_mask:0xf bound_ctrl:1
	v_add_f32_dpp v26, v26, v26 row_ror:8 row_mask:0xf bank_mask:0xf bound_ctrl:1
	ds_write_b32 v76, v26 offset:1280
	v_pk_fma_f32 v[8:9], v[118:119], v[0:1], v[12:13] op_sel_hi:[0,1,1]
	v_pk_fma_f32 v[10:11], v[118:119], v[0:1], v[14:15] op_sel:[1,0,0]
	v_pk_fma_f32 v[20:21], v[120:121], v[0:1], v[16:17] op_sel_hi:[0,1,1]
	v_pk_fma_f32 v[22:23], v[120:121], v[0:1], v[18:19] op_sel:[1,0,0]
	v_pk_mul_f32 v[4:5], v[8:9], v[122:123] op_sel_hi:[1,0]
	v_pk_mul_f32 v[6:7], v[10:11], v[122:123] op_sel:[0,1]
	v_pk_fma_f32 v[4:5], v[20:21], v[124:125], v[4:5] op_sel_hi:[1,0,1]
	v_pk_fma_f32 v[6:7], v[22:23], v[124:125], v[6:7] op_sel:[0,1,0]
	ds_read_b128 v[106:109], v74 offset:27904
	ds_read_b128 v[110:113], v74 offset:11520
	ds_read_b128 v[114:117], v74 offset:19712
	ds_read_b128 v[118:121], v74 offset:36096
	ds_read_b128 v[122:125], v74 offset:3328
	ds_read_b64 v[126:127], v75 offset:42624
	s_waitcnt lgkmcnt(7)
; __device__ __forceinline__ void rwkv_scan_phase(Frame& F, const bf16* RKV, const float* WAG, const bf16* AGB, const float* k_k, const float* k_a, const float* r_k, bf16* Y, float* BS, float* ST2) {
;     ...
;                 f32x2 r0[4], w0[4], k0[4], a0[4], b0[4], r1[4], w1[4], k1[4], a1[4], b1[4]; float v0, v1;
;                 SC_LOAD(r0, w0, k0, a0, b0, v0, 0);
; #pragma unroll
;                 for (int t = 0; t < SC_T; t += 2) {
;                     SC_LOAD(r1, w1, k1, a1, b1, v1, t + 1);
;                     SC_STEP(r0, w0, k0, a0, b0, v0, t);
;                     if (t + 2 < SC_T) SC_LOAD(r0, w0, k0, a0, b0, v0, t + 2);
;                     SC_STEP(r1, w1, k1, a1, b1, v1, t + 1);
;                 }
	v_pk_mul_f32 v[0:1], v[8:9], v[28:29] op_sel_hi:[1,0]
	v_pk_mul_f32 v[2:3], v[10:11], v[28:29] op_sel:[0,1]
	v_pk_fma_f32 v[0:1], v[20:21], v[30:31], v[0:1] op_sel_hi:[1,0,1]
	v_pk_fma_f32 v[2:3], v[22:23], v[30:31], v[2:3] op_sel:[0,1,0]
	v_pk_add_f32 v[4:5], v[4:5], v[6:7]
	v_pk_mul_f32 v[12:13], v[8:9], v[32:33] op_sel_hi:[1,0]
	v_pk_add_f32 v[0:1], v[0:1], v[2:3]
	v_pk_mul_f32 v[14:15], v[10:11], v[32:33] op_sel:[0,1]
	v_cndmask_b32_e32 v24, v4, v5, vcc
	v_cndmask_b32_e32 v25, v5, v4, vcc
	v_pk_mul_f32 v[16:17], v[20:21], v[34:35] op_sel_hi:[1,0]
	v_pk_mul_f32 v[18:19], v[22:23], v[34:35] op_sel:[0,1]
	v_add_f32_dpp v0, v0, v0 quad_perm:[1,0,3,2] row_mask:0xf bank_mask:0xf bound_ctrl:1
	v_add_f32_dpp v1, v1, v1 quad_perm:[1,0,3,2] row_mask:0xf bank_mask:0xf bound_ctrl:1
	v_add_f32_dpp v26, v25, v24 quad_perm:[1,0,3,2] row_mask:0xf bank_mask:0xf bound_ctrl:1
	v_pk_fma_f32 v[12:13], v[36:37], v[48:49], v[12:13] op_sel_hi:[0,1,1]
	v_pk_fma_f32 v[14:15], v[36:37], v[48:49], v[14:15] op_sel:[1,0,0]
	v_add_f32_dpp v0, v0, v0 quad_perm:[2,3,0,1] row_mask:0xf bank_mask:0xf bound_ctrl:1
	v_add_f32_dpp v1, v1, v1 quad_perm:[2,3,0,1] row_mask:0xf bank_mask:0xf bound_ctrl:1
	v_add_f32_dpp v26, v26, v26 quad_perm:[2,3,0,1] row_mask:0xf bank_mask:0xf bound_ctrl:1
	v_pk_fma_f32 v[16:17], v[38:39], v[48:49], v[16:17] op_sel_hi:[0,1,1]
	v_pk_fma_f32 v[18:19], v[38:39], v[48:49], v[18:19] op_sel:[1,0,0]
	v_add_f32_dpp v0, v0, v0 row_half_mirror row_mask:0xf bank_mask:0xf bound_ctrl:1
	v_add_f32_dpp v1, v1, v1 row_half_mirror row_mask:0xf bank_mask:0xf bound_ctrl:1
	v_add_f32_dpp v26, v26, v26 row_ror:4 row_mask:0xf bank_mask:0xf bound_ctrl:1
	s_nop 0
	v_add_f32_dpp v0, v0, v0 row_mirror row_mask:0xf bank_mask:0xf bound_ctrl:1
	v_add_f32_dpp v1, v1, v1 row_mirror row_mask:0xf bank_mask:0xf bound_ctrl:1
	v_add_f32_dpp v26, v26, v26 row_ror:8 row_mask:0xf bank_mask:0xf bound_ctrl:1
	ds_write_b32 v76, v26 offset:1408
	v_pk_fma_f32 v[8:9], v[40:41], v[0:1], v[12:13] op_sel_hi:[0,1,1]
	v_pk_fma_f32 v[10:11], v[40:41], v[0:1], v[14:15] op_sel:[1,0,0]
	v_pk_fma_f32 v[20:21], v[42:43], v[0:1], v[16:17] op_sel_hi:[0,1,1]
	v_pk_fma_f32 v[22:23], v[42:43], v[0:1], v[18:19] op_sel:[1,0,0]
	v_pk_mul_f32 v[4:5], v[8:9], v[44:45] op_sel_hi:[1,0]
	v_pk_mul_f32 v[6:7], v[10:11], v[44:45] op_sel:[0,1]
	v_pk_fma_f32 v[4:5], v[20:21], v[46:47], v[4:5] op_sel_hi:[1,0,1]
	v_pk_fma_f32 v[6:7], v[22:23], v[46:47], v[6:7] op_sel:[0,1,0]
	ds_read_b128 v[28:31], v74 offset:28160
	ds_read_b128 v[32:35], v74 offset:11776
	ds_read_b128 v[36:39], v74 offset:19968
	ds_read_b128 v[40:43], v74 offset:36352
	ds_read_b128 v[44:47], v74 offset:3584
	ds_read_b64 v[48:49], v75 offset:42752
	s_waitcnt lgkmcnt(7)
	v_pk_mul_f32 v[0:1], v[8:9], v[106:107] op_sel_hi:[1,0]
	v_pk_mul_f32 v[2:3], v[10:11], v[106:107] op_sel:[0,1]
	v_pk_fma_f32 v[0:1], v[20:21], v[108:109], v[0:1] op_sel_hi:[1,0,1]
	v_pk_fma_f32 v[2:3], v[22:23], v[108:109], v[2:3] op_sel:[0,1,0]
	v_pk_add_f32 v[4:5], v[4:5], v[6:7]
	v_pk_mul_f32 v[12:13], v[8:9], v[110:111] op_sel_hi:[1,0]
	v_pk_add_f32 v[0:1], v[0:1], v[2:3]
	v_pk_mul_f32 v[14:15], v[10:11], v[110:111] op_sel:[0,1]
	v_cndmask_b32_e32 v24, v4, v5, vcc
	v_cndmask_b32_e32 v25, v5, v4, vcc
	v_pk_mul_f32 v[16:17], v[20:21], v[112:113] op_sel_hi:[1,0]
	v_pk_mul_f32 v[18:19], v[22:23], v[112:113] op_sel:[0,1]
	v_add_f32_dpp v0, v0, v0 quad_perm:[1,0,3,2] row_mask:0xf bank_mask:0xf bound_ctrl:1
	v_add_f32_dpp v1, v1, v1 quad_perm:[1,0,3,2] row_mask:0xf bank_mask:0xf bound_ctrl:1
	v_add_f32_dpp v26, v25, v24 quad_perm:[1,0,3,2] row_mask:0xf bank_mask:0xf bound_ctrl:1
	v_pk_fma_f32 v[12:13], v[114:115], v[126:127], v[12:13] op_sel_hi:[0,1,1]
	v_pk_fma_f32 v[14:15], v[114:115], v[126:127], v[14:15] op_sel:[1,0,0]
	v_add_f32_dpp v0, v0, v0 quad_perm:[2,3,0,1] row_mask:0xf bank_mask:0xf bound_ctrl:1
	v_add_f32_dpp v1, v1, v1 quad_perm:[2,3,0,1] row_mask:0xf bank_mask:0xf bound_ctrl:1
	v_add_f32_dpp v26, v26, v26 quad_perm:[2,3,0,1] row_mask:0xf bank_mask:0xf bound_ctrl:1
	v_pk_fma_f32 v[16:17], v[116:117], v[126:127], v[16:17] op_sel_hi:[0,1,1]
	v_pk_fma_f32 v[18:19], v[116:117], v[126:127], v[18:19] op_sel:[1,0,0]
	v_add_f32_dpp v0, v0, v0 row_half_mirror row_mask:0xf bank_mask:0xf bound_ctrl:1
	v_add_f32_dpp v1, v1, v1 row_half_mirror row_mask:0xf bank_mask:0xf bound_ctrl:1
	v_add_f32_dpp v26, v26, v26 row_ror:4 row_mask:0xf bank_mask:0xf bound_ctrl:1
	s_nop 0
	v_add_f32_dpp v0, v0, v0 row_mirror row_mask:0xf bank_mask:0xf bound_ctrl:1
	v_add_f32_dpp v1, v1, v1 row_mirror row_mask:0xf bank_mask:0xf bound_ctrl:1
	v_add_f32_dpp v26, v26, v26 row_ror:8 row_mask:0xf bank_mask:0xf bound_ctrl:1
	ds_write_b32 v76, v26 offset:1536
	v_pk_fma_f32 v[8:9], v[118:119], v[0:1], v[12:13] op_sel_hi:[0,1,1]
	v_pk_fma_f32 v[10:11], v[118:119], v[0:1], v[14:15] op_sel:[1,0,0]
	v_pk_fma_f32 v[20:21], v[120:121], v[0:1], v[16:17] op_sel_hi:[0,1,1]
	v_pk_fma_f32 v[22:23], v[120:121], v[0:1], v[18:19] op_sel:[1,0,0]
	v_pk_mul_f32 v[4:5], v[8:9], v[122:123] op_sel_hi:[1,0]
	v_pk_mul_f32 v[6:7], v[10:11], v[122:123] op_sel:[0,1]
	v_pk_fma_f32 v[4:5], v[20:21], v[124:125], v[4:5] op_sel_hi:[1,0,1]
	v_pk_fma_f32 v[6:7], v[22:23], v[124:125], v[6:7] op_sel:[0,1,0]
	ds_read_b128 v[106:109], v74 offset:28416
	ds_read_b128 v[110:113], v74 offset:12032
	ds_read_b128 v[114:117], v74 offset:20224
	ds_read_b128 v[118:121], v74 offset:36608
	ds_read_b128 v[122:125], v74 offset:3840
	ds_read_b64 v[126:127], v75 offset:42880
	s_waitcnt lgkmcnt(7)
; __device__ __forceinline__ void rwkv_scan_phase(Frame& F, const bf16* RKV, const float* WAG, const bf16* AGB, const float* k_k, const float* k_a, const float* r_k, bf16* Y, float* BS, float* ST2) {
;     ...
;                 f32x2 r0[4], w0[4], k0[4], a0[4], b0[4], r1[4], w1[4], k1[4], a1[4], b1[4]; float v0, v1;
;                 SC_LOAD(r0, w0, k0, a0, b0, v0, 0);
; #pragma unroll
;                 for (int t = 0; t < SC_T; t += 2) {
;                     SC_LOAD(r1, w1, k1, a1, b1, v1, t + 1);
;                     SC_STEP(r0, w0, k0, a0, b0, v0, t);
;                     if (t + 2 < SC_T) SC_LOAD(r0, w0, k0, a0, b0, v0, t + 2);
;                     SC_STEP(r1, w1, k1, a1, b1, v1, t + 1);
;                 }
	v_pk_mul_f32 v[0:1], v[8:9], v[28:29] op_sel_hi:[1,0]
	v_pk_mul_f32 v[2:3], v[10:11], v[28:29] op_sel:[0,1]
	v_pk_fma_f32 v[0:1], v[20:21], v[30:31], v[0:1] op_sel_hi:[1,0,1]
	v_pk_fma_f32 v[2:3], v[22:23], v[30:31], v[2:3] op_sel:[0,1,0]
	v_pk_add_f32 v[4:5], v[4:5], v[6:7]
	v_pk_mul_f32 v[12:13], v[8:9], v[32:33] op_sel_hi:[1,0]
	v_pk_add_f32 v[0:1], v[0:1], v[2:3]
	v_pk_mul_f32 v[14:15], v[10:11], v[32:33] op_sel:[0,1]
	v_cndmask_b32_e32 v24, v4, v5, vcc
	v_cndmask_b32_e32 v25, v5, v4, vcc
	v_pk_mul_f32 v[16:17], v[20:21], v[34:35] op_sel_hi:[1,0]
	v_pk_mul_f32 v[18:19], v[22:23], v[34:35] op_sel:[0,1]
	v_add_f32_dpp v0, v0, v0 quad_perm:[1,0,3,2] row_mask:0xf bank_mask:0xf bound_ctrl:1
	v_add_f32_dpp v1, v1, v1 quad_perm:[1,0,3,2] row_mask:0xf bank_mask:0xf bound_ctrl:1
	v_add_f32_dpp v26, v25, v24 quad_perm:[1,0,3,2] row_mask:0xf bank_mask:0xf bound_ctrl:1
	v_pk_fma_f32 v[12:13], v[36:37], v[48:49], v[12:13] op_sel_hi:[0,1,1]
	v_pk_fma_f32 v[14:15], v[36:37], v[48:49], v[14:15] op_sel:[1,0,0]
	v_add_f32_dpp v0, v0, v0 quad_perm:[2,3,0,1] row_mask:0xf bank_mask:0xf bound_ctrl:1
	v_add_f32_dpp v1, v1, v1 quad_perm:[2,3,0,1] row_mask:0xf bank_mask:0xf bound_ctrl:1
	v_add_f32_dpp v26, v26, v26 quad_perm:[2,3,0,1] row_mask:0xf bank_mask:0xf bound_ctrl:1
	v_pk_fma_f32 v[16:17], v[38:39], v[48:49], v[16:17] op_sel_hi:[0,1,1]
	v_pk_fma_f32 v[18:19], v[38:39], v[48:49], v[18:19] op_sel:[1,0,0]
	v_add_f32_dpp v0, v0, v0 row_half_mirror row_mask:0xf bank_mask:0xf bound_ctrl:1
	v_add_f32_dpp v1, v1, v1 row_half_mirror row_mask:0xf bank_mask:0xf bound_ctrl:1
	v_add_f32_dpp v26, v26, v26 row_ror:4 row_mask:0xf bank_mask:0xf bound_ctrl:1
	s_nop 0
	v_add_f32_dpp v0, v0, v0 row_mirror row_mask:0xf bank_mask:0xf bound_ctrl:1
	v_add_f32_dpp v1, v1, v1 row_mirror row_mask:0xf bank_mask:0xf bound_ctrl:1
	v_add_f32_dpp v26, v26, v26 row_ror:8 row_mask:0xf bank_mask:0xf bound_ctrl:1
	ds_write_b32 v76, v26 offset:1664
	v_pk_fma_f32 v[8:9], v[40:41], v[0:1], v[12:13] op_sel_hi:[0,1,1]
	v_pk_fma_f32 v[10:11], v[40:41], v[0:1], v[14:15] op_sel:[1,0,0]
	v_pk_fma_f32 v[20:21], v[42:43], v[0:1], v[16:17] op_sel_hi:[0,1,1]
	v_pk_fma_f32 v[22:23], v[42:43], v[0:1], v[18:19] op_sel:[1,0,0]
	v_pk_mul_f32 v[4:5], v[8:9], v[44:45] op_sel_hi:[1,0]
	v_pk_mul_f32 v[6:7], v[10:11], v[44:45] op_sel:[0,1]
	v_pk_fma_f32 v[4:5], v[20:21], v[46:47], v[4:5] op_sel_hi:[1,0,1]
	v_pk_fma_f32 v[6:7], v[22:23], v[46:47], v[6:7] op_sel:[0,1,0]
	ds_read_b128 v[28:31], v74 offset:28672
	ds_read_b128 v[32:35], v74 offset:12288
	ds_read_b128 v[36:39], v74 offset:20480
	ds_read_b128 v[40:43], v74 offset:36864
	ds_read_b128 v[44:47], v74 offset:4096
	ds_read_b64 v[48:49], v75 offset:43008
	s_waitcnt lgkmcnt(7)
	v_pk_mul_f32 v[0:1], v[8:9], v[106:107] op_sel_hi:[1,0]
	v_pk_mul_f32 v[2:3], v[10:11], v[106:107] op_sel:[0,1]
	v_pk_fma_f32 v[0:1], v[20:21], v[108:109], v[0:1] op_sel_hi:[1,0,1]
	v_pk_fma_f32 v[2:3], v[22:23], v[108:109], v[2:3] op_sel:[0,1,0]
	v_pk_add_f32 v[4:5], v[4:5], v[6:7]
	v_pk_mul_f32 v[12:13], v[8:9], v[110:111] op_sel_hi:[1,0]
	v_pk_add_f32 v[0:1], v[0:1], v[2:3]
	v_pk_mul_f32 v[14:15], v[10:11], v[110:111] op_sel:[0,1]
	v_cndmask_b32_e32 v24, v4, v5, vcc
	v_cndmask_b32_e32 v25, v5, v4, vcc
	v_pk_mul_f32 v[16:17], v[20:21], v[112:113] op_sel_hi:[1,0]
	v_pk_mul_f32 v[18:19], v[22:23], v[112:113] op_sel:[0,1]
	v_add_f32_dpp v0, v0, v0 quad_perm:[1,0,3,2] row_mask:0xf bank_mask:0xf bound_ctrl:1
	v_add_f32_dpp v1, v1, v1 quad_perm:[1,0,3,2] row_mask:0xf bank_mask:0xf bound_ctrl:1
	v_add_f32_dpp v26, v25, v24 quad_perm:[1,0,3,2] row_mask:0xf bank_mask:0xf bound_ctrl:1
	v_pk_fma_f32 v[12:13], v[114:115], v[126:127], v[12:13] op_sel_hi:[0,1,1]
	v_pk_fma_f32 v[14:15], v[114:115], v[126:127], v[14:15] op_sel:[1,0,0]
	v_add_f32_dpp v0, v0, v0 quad_perm:[2,3,0,1] row_mask:0xf bank_mask:0xf bound_ctrl:1
	v_add_f32_dpp v1, v1, v1 quad_perm:[2,3,0,1] row_mask:0xf bank_mask:0xf bound_ctrl:1
	v_add_f32_dpp v26, v26, v26 quad_perm:[2,3,0,1] row_mask:0xf bank_mask:0xf bound_ctrl:1
	v_pk_fma_f32 v[16:17], v[116:117], v[126:127], v[16:17] op_sel_hi:[0,1,1]
	v_pk_fma_f32 v[18:19], v[116:117], v[126:127], v[18:19] op_sel:[1,0,0]
	v_add_f32_dpp v0, v0, v0 row_half_mirror row_mask:0xf bank_mask:0xf bound_ctrl:1
	v_add_f32_dpp v1, v1, v1 row_half_mirror row_mask:0xf bank_mask:0xf bound_ctrl:1
	v_add_f32_dpp v26, v26, v26 row_ror:4 row_mask:0xf bank_mask:0xf bound_ctrl:1
	s_nop 0
	v_add_f32_dpp v0, v0, v0 row_mirror row_mask:0xf bank_mask:0xf bound_ctrl:1
	v_add_f32_dpp v1, v1, v1 row_mirror row_mask:0xf bank_mask:0xf bound_ctrl:1
	v_add_f32_dpp v26, v26, v26 row_ror:8 row_mask:0xf bank_mask:0xf bound_ctrl:1
	ds_write_b32 v76, v26 offset:1792
	v_pk_fma_f32 v[8:9], v[118:119], v[0:1], v[12:13] op_sel_hi:[0,1,1]
	v_pk_fma_f32 v[10:11], v[118:119], v[0:1], v[14:15] op_sel:[1,0,0]
	v_pk_fma_f32 v[20:21], v[120:121], v[0:1], v[16:17] op_sel_hi:[0,1,1]
	v_pk_fma_f32 v[22:23], v[120:121], v[0:1], v[18:19] op_sel:[1,0,0]
	v_pk_mul_f32 v[4:5], v[8:9], v[122:123] op_sel_hi:[1,0]
	v_pk_mul_f32 v[6:7], v[10:11], v[122:123] op_sel:[0,1]
	v_pk_fma_f32 v[4:5], v[20:21], v[124:125], v[4:5] op_sel_hi:[1,0,1]
	v_pk_fma_f32 v[6:7], v[22:23], v[124:125], v[6:7] op_sel:[0,1,0]
	ds_read_b128 v[106:109], v74 offset:28928
	ds_read_b128 v[110:113], v74 offset:12544
	ds_read_b128 v[114:117], v74 offset:20736
	ds_read_b128 v[118:121], v74 offset:37120
	ds_read_b128 v[122:125], v74 offset:4352
	ds_read_b64 v[126:127], v75 offset:43136
	s_waitcnt lgkmcnt(7)
; __device__ __forceinline__ void rwkv_scan_phase(Frame& F, const bf16* RKV, const float* WAG, const bf16* AGB, const float* k_k, const float* k_a, const float* r_k, bf16* Y, float* BS, float* ST2) {
;     ...
;                 f32x2 r0[4], w0[4], k0[4], a0[4], b0[4], r1[4], w1[4], k1[4], a1[4], b1[4]; float v0, v1;
;                 SC_LOAD(r0, w0, k0, a0, b0, v0, 0);
; #pragma unroll
;                 for (int t = 0; t < SC_T; t += 2) {
;                     SC_LOAD(r1, w1, k1, a1, b1, v1, t + 1);
;                     SC_STEP(r0, w0, k0, a0, b0, v0, t);
;                     if (t + 2 < SC_T) SC_LOAD(r0, w0, k0, a0, b0, v0, t + 2);
;                     SC_STEP(r1, w1, k1, a1, b1, v1, t + 1);
;                 }
	v_pk_mul_f32 v[0:1], v[8:9], v[28:29] op_sel_hi:[1,0]
	v_pk_mul_f32 v[2:3], v[10:11], v[28:29] op_sel:[0,1]
	v_pk_fma_f32 v[0:1], v[20:21], v[30:31], v[0:1] op_sel_hi:[1,0,1]
	v_pk_fma_f32 v[2:3], v[22:23], v[30:31], v[2:3] op_sel:[0,1,0]
	v_pk_add_f32 v[4:5], v[4:5], v[6:7]
	v_pk_mul_f32 v[12:13], v[8:9], v[32:33] op_sel_hi:[1,0]
	v_pk_add_f32 v[0:1], v[0:1], v[2:3]
	v_pk_mul_f32 v[14:15], v[10:11], v[32:33] op_sel:[0,1]
	v_cndmask_b32_e32 v24, v4, v5, vcc
	v_cndmask_b32_e32 v25, v5, v4, vcc
	v_pk_mul_f32 v[16:17], v[20:21], v[34:35] op_sel_hi:[1,0]
	v_pk_mul_f32 v[18:19], v[22:23], v[34:35] op_sel:[0,1]
	v_add_f32_dpp v0, v0, v0 quad_perm:[1,0,3,2] row_mask:0xf bank_mask:0xf bound_ctrl:1
	v_add_f32_dpp v1, v1, v1 quad_perm:[1,0,3,2] row_mask:0xf bank_mask:0xf bound_ctrl:1
	v_add_f32_dpp v26, v25, v24 quad_perm:[1,0,3,2] row_mask:0xf bank_mask:0xf bound_ctrl:1
	v_pk_fma_f32 v[12:13], v[36:37], v[48:49], v[12:13] op_sel_hi:[0,1,1]
	v_pk_fma_f32 v[14:15], v[36:37], v[48:49], v[14:15] op_sel:[1,0,0]
	v_add_f32_dpp v0, v0, v0 quad_perm:[2,3,0,1] row_mask:0xf bank_mask:0xf bound_ctrl:1
	v_add_f32_dpp v1, v1, v1 quad_perm:[2,3,0,1] row_mask:0xf bank_mask:0xf bound_ctrl:1
	v_add_f32_dpp v26, v26, v26 quad_perm:[2,3,0,1] row_mask:0xf bank_mask:0xf bound_ctrl:1
	v_pk_fma_f32 v[16:17], v[38:39], v[48:49], v[16:17] op_sel_hi:[0,1,1]
	v_pk_fma_f32 v[18:19], v[38:39], v[48:49], v[18:19] op_sel:[1,0,0]
	v_add_f32_dpp v0, v0, v0 row_half_mirror row_mask:0xf bank_mask:0xf bound_ctrl:1
	v_add_f32_dpp v1, v1, v1 row_half_mirror row_mask:0xf bank_mask:0xf bound_ctrl:1
	v_add_f32_dpp v26, v26, v26 row_ror:4 row_mask:0xf bank_mask:0xf bound_ctrl:1
	s_nop 0
	v_add_f32_dpp v0, v0, v0 row_mirror row_mask:0xf bank_mask:0xf bound_ctrl:1
	v_add_f32_dpp v1, v1, v1 row_mirror row_mask:0xf bank_mask:0xf bound_ctrl:1
	v_add_f32_dpp v26, v26, v26 row_ror:8 row_mask:0xf bank_mask:0xf bound_ctrl:1
	ds_write_b32 v76, v26 offset:1920
	v_pk_fma_f32 v[8:9], v[40:41], v[0:1], v[12:13] op_sel_hi:[0,1,1]
	v_pk_fma_f32 v[10:11], v[40:41], v[0:1], v[14:15] op_sel:[1,0,0]
	v_pk_fma_f32 v[20:21], v[42:43], v[0:1], v[16:17] op_sel_hi:[0,1,1]
	v_pk_fma_f32 v[22:23], v[42:43], v[0:1], v[18:19] op_sel:[1,0,0]
	v_pk_mul_f32 v[4:5], v[8:9], v[44:45] op_sel_hi:[1,0]
	v_pk_mul_f32 v[6:7], v[10:11], v[44:45] op_sel:[0,1]
	v_pk_fma_f32 v[4:5], v[20:21], v[46:47], v[4:5] op_sel_hi:[1,0,1]
	v_pk_fma_f32 v[6:7], v[22:23], v[46:47], v[6:7] op_sel:[0,1,0]
	ds_read_b128 v[28:31], v74 offset:29184
	ds_read_b128 v[32:35], v74 offset:12800
	ds_read_b128 v[36:39], v74 offset:20992
	ds_read_b128 v[40:43], v74 offset:37376
	ds_read_b128 v[44:47], v74 offset:4608
	ds_read_b64 v[48:49], v75 offset:43264
	s_waitcnt lgkmcnt(7)
	v_pk_mul_f32 v[0:1], v[8:9], v[106:107] op_sel_hi:[1,0]
	v_pk_mul_f32 v[2:3], v[10:11], v[106:107] op_sel:[0,1]
	v_pk_fma_f32 v[0:1], v[20:21], v[108:109], v[0:1] op_sel_hi:[1,0,1]
	v_pk_fma_f32 v[2:3], v[22:23], v[108:109], v[2:3] op_sel:[0,1,0]
	v_pk_add_f32 v[4:5], v[4:5], v[6:7]
	v_pk_mul_f32 v[12:13], v[8:9], v[110:111] op_sel_hi:[1,0]
	v_pk_add_f32 v[0:1], v[0:1], v[2:3]
	v_pk_mul_f32 v[14:15], v[10:11], v[110:111] op_sel:[0,1]
	v_cndmask_b32_e32 v24, v4, v5, vcc
	v_cndmask_b32_e32 v25, v5, v4, vcc
	v_pk_mul_f32 v[16:17], v[20:21], v[112:113] op_sel_hi:[1,0]
	v_pk_mul_f32 v[18:19], v[22:23], v[112:113] op_sel:[0,1]
	v_add_f32_dpp v0, v0, v0 quad_perm:[1,0,3,2] row_mask:0xf bank_mask:0xf bound_ctrl:1
	v_add_f32_dpp v1, v1, v1 quad_perm:[1,0,3,2] row_mask:0xf bank_mask:0xf bound_ctrl:1
	v_add_f32_dpp v26, v25, v24 quad_perm:[1,0,3,2] row_mask:0xf bank_mask:0xf bound_ctrl:1
	v_pk_fma_f32 v[12:13], v[114:115], v[126:127], v[12:13] op_sel_hi:[0,1,1]
	v_pk_fma_f32 v[14:15], v[114:115], v[126:127], v[14:15] op_sel:[1,0,0]
	v_add_f32_dpp v0, v0, v0 quad_perm:[2,3,0,1] row_mask:0xf bank_mask:0xf bound_ctrl:1
	v_add_f32_dpp v1, v1, v1 quad_perm:[2,3,0,1] row_mask:0xf bank_mask:0xf bound_ctrl:1
	v_add_f32_dpp v26, v26, v26 quad_perm:[2,3,0,1] row_mask:0xf bank_mask:0xf bound_ctrl:1
	v_pk_fma_f32 v[16:17], v[116:117], v[126:127], v[16:17] op_sel_hi:[0,1,1]
	v_pk_fma_f32 v[18:19], v[116:117], v[126:127], v[18:19] op_sel:[1,0,0]
	v_add_f32_dpp v0, v0, v0 row_half_mirror row_mask:0xf bank_mask:0xf bound_ctrl:1
	v_add_f32_dpp v1, v1, v1 row_half_mirror row_mask:0xf bank_mask:0xf bound_ctrl:1
	v_add_f32_dpp v26, v26, v26 row_ror:4 row_mask:0xf bank_mask:0xf bound_ctrl:1
	s_nop 0
	v_add_f32_dpp v0, v0, v0 row_mirror row_mask:0xf bank_mask:0xf bound_ctrl:1
	v_add_f32_dpp v1, v1, v1 row_mirror row_mask:0xf bank_mask:0xf bound_ctrl:1
	v_add_f32_dpp v26, v26, v26 row_ror:8 row_mask:0xf bank_mask:0xf bound_ctrl:1
	ds_write_b32 v76, v26 offset:2048
	v_pk_fma_f32 v[8:9], v[118:119], v[0:1], v[12:13] op_sel_hi:[0,1,1]
	v_pk_fma_f32 v[10:11], v[118:119], v[0:1], v[14:15] op_sel:[1,0,0]
	v_pk_fma_f32 v[20:21], v[120:121], v[0:1], v[16:17] op_sel_hi:[0,1,1]
	v_pk_fma_f32 v[22:23], v[120:121], v[0:1], v[18:19] op_sel:[1,0,0]
	v_pk_mul_f32 v[4:5], v[8:9], v[122:123] op_sel_hi:[1,0]
	v_pk_mul_f32 v[6:7], v[10:11], v[122:123] op_sel:[0,1]
	v_pk_fma_f32 v[4:5], v[20:21], v[124:125], v[4:5] op_sel_hi:[1,0,1]
	v_pk_fma_f32 v[6:7], v[22:23], v[124:125], v[6:7] op_sel:[0,1,0]
	ds_read_b128 v[106:109], v74 offset:29440
	ds_read_b128 v[110:113], v74 offset:13056
	ds_read_b128 v[114:117], v74 offset:21248
	ds_read_b128 v[118:121], v74 offset:37632
	ds_read_b128 v[122:125], v74 offset:4864
	ds_read_b64 v[126:127], v75 offset:43392
	s_waitcnt lgkmcnt(7)
; __device__ __forceinline__ void rwkv_scan_phase(Frame& F, const bf16* RKV, const float* WAG, const bf16* AGB, const float* k_k, const float* k_a, const float* r_k, bf16* Y, float* BS, float* ST2) {
;     ...
;                 f32x2 r0[4], w0[4], k0[4], a0[4], b0[4], r1[4], w1[4], k1[4], a1[4], b1[4]; float v0, v1;
;                 SC_LOAD(r0, w0, k0, a0, b0, v0, 0);
; #pragma unroll
;                 for (int t = 0; t < SC_T; t += 2) {
;                     SC_LOAD(r1, w1, k1, a1, b1, v1, t + 1);
;                     SC_STEP(r0, w0, k0, a0, b0, v0, t);
;                     if (t + 2 < SC_T) SC_LOAD(r0, w0, k0, a0, b0, v0, t + 2);
;                     SC_STEP(r1, w1, k1, a1, b1, v1, t + 1);
;                 }
	v_pk_mul_f32 v[0:1], v[8:9], v[28:29] op_sel_hi:[1,0]
	v_pk_mul_f32 v[2:3], v[10:11], v[28:29] op_sel:[0,1]
	v_pk_fma_f32 v[0:1], v[20:21], v[30:31], v[0:1] op_sel_hi:[1,0,1]
	v_pk_fma_f32 v[2:3], v[22:23], v[30:31], v[2:3] op_sel:[0,1,0]
	v_pk_add_f32 v[4:5], v[4:5], v[6:7]
	v_pk_mul_f32 v[12:13], v[8:9], v[32:33] op_sel_hi:[1,0]
	v_pk_add_f32 v[0:1], v[0:1], v[2:3]
	v_pk_mul_f32 v[14:15], v[10:11], v[32:33] op_sel:[0,1]
	v_cndmask_b32_e32 v24, v4, v5, vcc
	v_cndmask_b32_e32 v25, v5, v4, vcc
	v_pk_mul_f32 v[16:17], v[20:21], v[34:35] op_sel_hi:[1,0]
	v_pk_mul_f32 v[18:19], v[22:23], v[34:35] op_sel:[0,1]
	v_add_f32_dpp v0, v0, v0 quad_perm:[1,0,3,2] row_mask:0xf bank_mask:0xf bound_ctrl:1
	v_add_f32_dpp v1, v1, v1 quad_perm:[1,0,3,2] row_mask:0xf bank_mask:0xf bound_ctrl:1
	v_add_f32_dpp v26, v25, v24 quad_perm:[1,0,3,2] row_mask:0xf bank_mask:0xf bound_ctrl:1
	v_pk_fma_f32 v[12:13], v[36:37], v[48:49], v[12:13] op_sel_hi:[0,1,1]
	v_pk_fma_f32 v[14:15], v[36:37], v[48:49], v[14:15] op_sel:[1,0,0]
	v_add_f32_dpp v0, v0, v0 quad_perm:[2,3,0,1] row_mask:0xf bank_mask:0xf bound_ctrl:1
	v_add_f32_dpp v1, v1, v1 quad_perm:[2,3,0,1] row_mask:0xf bank_mask:0xf bound_ctrl:1
	v_add_f32_dpp v26, v26, v26 quad_perm:[2,3,0,1] row_mask:0xf bank_mask:0xf bound_ctrl:1
	v_pk_fma_f32 v[16:17], v[38:39], v[48:49], v[16:17] op_sel_hi:[0,1,1]
	v_pk_fma_f32 v[18:19], v[38:39], v[48:49], v[18:19] op_sel:[1,0,0]
	v_add_f32_dpp v0, v0, v0 row_half_mirror row_mask:0xf bank_mask:0xf bound_ctrl:1
	v_add_f32_dpp v1, v1, v1 row_half_mirror row_mask:0xf bank_mask:0xf bound_ctrl:1
	v_add_f32_dpp v26, v26, v26 row_ror:4 row_mask:0xf bank_mask:0xf bound_ctrl:1
	s_nop 0
	v_add_f32_dpp v0, v0, v0 row_mirror row_mask:0xf bank_mask:0xf bound_ctrl:1
	v_add_f32_dpp v1, v1, v1 row_mirror row_mask:0xf bank_mask:0xf bound_ctrl:1
	v_add_f32_dpp v26, v26, v26 row_ror:8 row_mask:0xf bank_mask:0xf bound_ctrl:1
	ds_write_b32 v76, v26 offset:2176
	v_pk_fma_f32 v[8:9], v[40:41], v[0:1], v[12:13] op_sel_hi:[0,1,1]
	v_pk_fma_f32 v[10:11], v[40:41], v[0:1], v[14:15] op_sel:[1,0,0]
	v_pk_fma_f32 v[20:21], v[42:43], v[0:1], v[16:17] op_sel_hi:[0,1,1]
	v_pk_fma_f32 v[22:23], v[42:43], v[0:1], v[18:19] op_sel:[1,0,0]
	v_pk_mul_f32 v[4:5], v[8:9], v[44:45] op_sel_hi:[1,0]
	v_pk_mul_f32 v[6:7], v[10:11], v[44:45] op_sel:[0,1]
	v_pk_fma_f32 v[4:5], v[20:21], v[46:47], v[4:5] op_sel_hi:[1,0,1]
	v_pk_fma_f32 v[6:7], v[22:23], v[46:47], v[6:7] op_sel:[0,1,0]
	ds_read_b128 v[28:31], v74 offset:29696
	ds_read_b128 v[32:35], v74 offset:13312
	ds_read_b128 v[36:39], v74 offset:21504
	ds_read_b128 v[40:43], v74 offset:37888
	ds_read_b128 v[44:47], v74 offset:5120
	ds_read_b64 v[48:49], v75 offset:43520
	s_waitcnt lgkmcnt(7)
	v_pk_mul_f32 v[0:1], v[8:9], v[106:107] op_sel_hi:[1,0]
	v_pk_mul_f32 v[2:3], v[10:11], v[106:107] op_sel:[0,1]
	v_pk_fma_f32 v[0:1], v[20:21], v[108:109], v[0:1] op_sel_hi:[1,0,1]
	v_pk_fma_f32 v[2:3], v[22:23], v[108:109], v[2:3] op_sel:[0,1,0]
	v_pk_add_f32 v[4:5], v[4:5], v[6:7]
	v_pk_mul_f32 v[12:13], v[8:9], v[110:111] op_sel_hi:[1,0]
	v_pk_add_f32 v[0:1], v[0:1], v[2:3]
	v_pk_mul_f32 v[14:15], v[10:11], v[110:111] op_sel:[0,1]
	v_cndmask_b32_e32 v24, v4, v5, vcc
	v_cndmask_b32_e32 v25, v5, v4, vcc
	v_pk_mul_f32 v[16:17], v[20:21], v[112:113] op_sel_hi:[1,0]
	v_pk_mul_f32 v[18:19], v[22:23], v[112:113] op_sel:[0,1]
	v_add_f32_dpp v0, v0, v0 quad_perm:[1,0,3,2] row_mask:0xf bank_mask:0xf bound_ctrl:1
	v_add_f32_dpp v1, v1, v1 quad_perm:[1,0,3,2] row_mask:0xf bank_mask:0xf bound_ctrl:1
	v_add_f32_dpp v26, v25, v24 quad_perm:[1,0,3,2] row_mask:0xf bank_mask:0xf bound_ctrl:1
	v_pk_fma_f32 v[12:13], v[114:115], v[126:127], v[12:13] op_sel_hi:[0,1,1]
	v_pk_fma_f32 v[14:15], v[114:115], v[126:127], v[14:15] op_sel:[1,0,0]
	v_add_f32_dpp v0, v0, v0 quad_perm:[2,3,0,1] row_mask:0xf bank_mask:0xf bound_ctrl:1
	v_add_f32_dpp v1, v1, v1 quad_perm:[2,3,0,1] row_mask:0xf bank_mask:0xf bound_ctrl:1
	v_add_f32_dpp v26, v26, v26 quad_perm:[2,3,0,1] row_mask:0xf bank_mask:0xf bound_ctrl:1
	v_pk_fma_f32 v[16:17], v[116:117], v[126:127], v[16:17] op_sel_hi:[0,1,1]
	v_pk_fma_f32 v[18:19], v[116:117], v[126:127], v[18:19] op_sel:[1,0,0]
	v_add_f32_dpp v0, v0, v0 row_half_mirror row_mask:0xf bank_mask:0xf bound_ctrl:1
	v_add_f32_dpp v1, v1, v1 row_half_mirror row_mask:0xf bank_mask:0xf bound_ctrl:1
	v_add_f32_dpp v26, v26, v26 row_ror:4 row_mask:0xf bank_mask:0xf bound_ctrl:1
	s_nop 0
	v_add_f32_dpp v0, v0, v0 row_mirror row_mask:0xf bank_mask:0xf bound_ctrl:1
	v_add_f32_dpp v1, v1, v1 row_mirror row_mask:0xf bank_mask:0xf bound_ctrl:1
	v_add_f32_dpp v26, v26, v26 row_ror:8 row_mask:0xf bank_mask:0xf bound_ctrl:1
	ds_write_b32 v76, v26 offset:2304
	v_pk_fma_f32 v[8:9], v[118:119], v[0:1], v[12:13] op_sel_hi:[0,1,1]
	v_pk_fma_f32 v[10:11], v[118:119], v[0:1], v[14:15] op_sel:[1,0,0]
	v_pk_fma_f32 v[20:21], v[120:121], v[0:1], v[16:17] op_sel_hi:[0,1,1]
	v_pk_fma_f32 v[22:23], v[120:121], v[0:1], v[18:19] op_sel:[1,0,0]
	v_pk_mul_f32 v[4:5], v[8:9], v[122:123] op_sel_hi:[1,0]
	v_pk_mul_f32 v[6:7], v[10:11], v[122:123] op_sel:[0,1]
	v_pk_fma_f32 v[4:5], v[20:21], v[124:125], v[4:5] op_sel_hi:[1,0,1]
	v_pk_fma_f32 v[6:7], v[22:23], v[124:125], v[6:7] op_sel:[0,1,0]
	ds_read_b128 v[106:109], v74 offset:29952
	ds_read_b128 v[110:113], v74 offset:13568
	ds_read_b128 v[114:117], v74 offset:21760
	ds_read_b128 v[118:121], v74 offset:38144
	ds_read_b128 v[122:125], v74 offset:5376
	ds_read_b64 v[126:127], v75 offset:43648
	s_waitcnt lgkmcnt(7)
; __device__ __forceinline__ void rwkv_scan_phase(Frame& F, const bf16* RKV, const float* WAG, const bf16* AGB, const float* k_k, const float* k_a, const float* r_k, bf16* Y, float* BS, float* ST2) {
;     ...
;                 f32x2 r0[4], w0[4], k0[4], a0[4], b0[4], r1[4], w1[4], k1[4], a1[4], b1[4]; float v0, v1;
;                 SC_LOAD(r0, w0, k0, a0, b0, v0, 0);
; #pragma unroll
;                 for (int t = 0; t < SC_T; t += 2) {
;                     SC_LOAD(r1, w1, k1, a1, b1, v1, t + 1);
;                     SC_STEP(r0, w0, k0, a0, b0, v0, t);
;                     if (t + 2 < SC_T) SC_LOAD(r0, w0, k0, a0, b0, v0, t + 2);
;                     SC_STEP(r1, w1, k1, a1, b1, v1, t + 1);
;                 }
	v_pk_mul_f32 v[0:1], v[8:9], v[28:29] op_sel_hi:[1,0]
	v_pk_mul_f32 v[2:3], v[10:11], v[28:29] op_sel:[0,1]
	v_pk_fma_f32 v[0:1], v[20:21], v[30:31], v[0:1] op_sel_hi:[1,0,1]
	v_pk_fma_f32 v[2:3], v[22:23], v[30:31], v[2:3] op_sel:[0,1,0]
	v_pk_add_f32 v[4:5], v[4:5], v[6:7]
	v_pk_mul_f32 v[12:13], v[8:9], v[32:33] op_sel_hi:[1,0]
	v_pk_add_f32 v[0:1], v[0:1], v[2:3]
	v_pk_mul_f32 v[14:15], v[10:11], v[32:33] op_sel:[0,1]
	v_cndmask_b32_e32 v24, v4, v5, vcc
	v_cndmask_b32_e32 v25, v5, v4, vcc
	v_pk_mul_f32 v[16:17], v[20:21], v[34:35] op_sel_hi:[1,0]
	v_pk_mul_f32 v[18:19], v[22:23], v[34:35] op_sel:[0,1]
	v_add_f32_dpp v0, v0, v0 quad_perm:[1,0,3,2] row_mask:0xf bank_mask:0xf bound_ctrl:1
	v_add_f32_dpp v1, v1, v1 quad_perm:[1,0,3,2] row_mask:0xf bank_mask:0xf bound_ctrl:1
	v_add_f32_dpp v26, v25, v24 quad_perm:[1,0,3,2] row_mask:0xf bank_mask:0xf bound_ctrl:1
	v_pk_fma_f32 v[12:13], v[36:37], v[48:49], v[12:13] op_sel_hi:[0,1,1]
	v_pk_fma_f32 v[14:15], v[36:37], v[48:49], v[14:15] op_sel:[1,0,0]
	v_add_f32_dpp v0, v0, v0 quad_perm:[2,3,0,1] row_mask:0xf bank_mask:0xf bound_ctrl:1
	v_add_f32_dpp v1, v1, v1 quad_perm:[2,3,0,1] row_mask:0xf bank_mask:0xf bound_ctrl:1
	v_add_f32_dpp v26, v26, v26 quad_perm:[2,3,0,1] row_mask:0xf bank_mask:0xf bound_ctrl:1
	v_pk_fma_f32 v[16:17], v[38:39], v[48:49], v[16:17] op_sel_hi:[0,1,1]
	v_pk_fma_f32 v[18:19], v[38:39], v[48:49], v[18:19] op_sel:[1,0,0]
	v_add_f32_dpp v0, v0, v0 row_half_mirror row_mask:0xf bank_mask:0xf bound_ctrl:1
	v_add_f32_dpp v1, v1, v1 row_half_mirror row_mask:0xf bank_mask:0xf bound_ctrl:1
	v_add_f32_dpp v26, v26, v26 row_ror:4 row_mask:0xf bank_mask:0xf bound_ctrl:1
	s_nop 0
	v_add_f32_dpp v0, v0, v0 row_mirror row_mask:0xf bank_mask:0xf bound_ctrl:1
	v_add_f32_dpp v1, v1, v1 row_mirror row_mask:0xf bank_mask:0xf bound_ctrl:1
	v_add_f32_dpp v26, v26, v26 row_ror:8 row_mask:0xf bank_mask:0xf bound_ctrl:1
	ds_write_b32 v76, v26 offset:2432
	v_pk_fma_f32 v[8:9], v[40:41], v[0:1], v[12:13] op_sel_hi:[0,1,1]
	v_pk_fma_f32 v[10:11], v[40:41], v[0:1], v[14:15] op_sel:[1,0,0]
	v_pk_fma_f32 v[20:21], v[42:43], v[0:1], v[16:17] op_sel_hi:[0,1,1]
	v_pk_fma_f32 v[22:23], v[42:43], v[0:1], v[18:19] op_sel:[1,0,0]
	v_pk_mul_f32 v[4:5], v[8:9], v[44:45] op_sel_hi:[1,0]
	v_pk_mul_f32 v[6:7], v[10:11], v[44:45] op_sel:[0,1]
	v_pk_fma_f32 v[4:5], v[20:21], v[46:47], v[4:5] op_sel_hi:[1,0,1]
	v_pk_fma_f32 v[6:7], v[22:23], v[46:47], v[6:7] op_sel:[0,1,0]
	ds_read_b128 v[28:31], v74 offset:30208
	ds_read_b128 v[32:35], v74 offset:13824
	ds_read_b128 v[36:39], v74 offset:22016
	ds_read_b128 v[40:43], v74 offset:38400
	ds_read_b128 v[44:47], v74 offset:5632
	ds_read_b64 v[48:49], v75 offset:43776
	s_waitcnt lgkmcnt(7)
	v_pk_mul_f32 v[0:1], v[8:9], v[106:107] op_sel_hi:[1,0]
	v_pk_mul_f32 v[2:3], v[10:11], v[106:107] op_sel:[0,1]
	v_pk_fma_f32 v[0:1], v[20:21], v[108:109], v[0:1] op_sel_hi:[1,0,1]
	v_pk_fma_f32 v[2:3], v[22:23], v[108:109], v[2:3] op_sel:[0,1,0]
	v_pk_add_f32 v[4:5], v[4:5], v[6:7]
	v_pk_mul_f32 v[12:13], v[8:9], v[110:111] op_sel_hi:[1,0]
	v_pk_add_f32 v[0:1], v[0:1], v[2:3]
	v_pk_mul_f32 v[14:15], v[10:11], v[110:111] op_sel:[0,1]
	v_cndmask_b32_e32 v24, v4, v5, vcc
	v_cndmask_b32_e32 v25, v5, v4, vcc
	v_pk_mul_f32 v[16:17], v[20:21], v[112:113] op_sel_hi:[1,0]
	v_pk_mul_f32 v[18:19], v[22:23], v[112:113] op_sel:[0,1]
	v_add_f32_dpp v0, v0, v0 quad_perm:[1,0,3,2] row_mask:0xf bank_mask:0xf bound_ctrl:1
	v_add_f32_dpp v1, v1, v1 quad_perm:[1,0,3,2] row_mask:0xf bank_mask:0xf bound_ctrl:1
	v_add_f32_dpp v26, v25, v24 quad_perm:[1,0,3,2] row_mask:0xf bank_mask:0xf bound_ctrl:1
	v_pk_fma_f32 v[12:13], v[114:115], v[126:127], v[12:13] op_sel_hi:[0,1,1]
	v_pk_fma_f32 v[14:15], v[114:115], v[126:127], v[14:15] op_sel:[1,0,0]
	v_add_f32_dpp v0, v0, v0 quad_perm:[2,3,0,1] row_mask:0xf bank_mask:0xf bound_ctrl:1
	v_add_f32_dpp v1, v1, v1 quad_perm:[2,3,0,1] row_mask:0xf bank_mask:0xf bound_ctrl:1
	v_add_f32_dpp v26, v26, v26 quad_perm:[2,3,0,1] row_mask:0xf bank_mask:0xf bound_ctrl:1
	v_pk_fma_f32 v[16:17], v[116:117], v[126:127], v[16:17] op_sel_hi:[0,1,1]
	v_pk_fma_f32 v[18:19], v[116:117], v[126:127], v[18:19] op_sel:[1,0,0]
	v_add_f32_dpp v0, v0, v0 row_half_mirror row_mask:0xf bank_mask:0xf bound_ctrl:1
	v_add_f32_dpp v1, v1, v1 row_half_mirror row_mask:0xf bank_mask:0xf bound_ctrl:1
	v_add_f32_dpp v26, v26, v26 row_ror:4 row_mask:0xf bank_mask:0xf bound_ctrl:1
	s_nop 0
	v_add_f32_dpp v0, v0, v0 row_mirror row_mask:0xf bank_mask:0xf bound_ctrl:1
	v_add_f32_dpp v1, v1, v1 row_mirror row_mask:0xf bank_mask:0xf bound_ctrl:1
	v_add_f32_dpp v26, v26, v26 row_ror:8 row_mask:0xf bank_mask:0xf bound_ctrl:1
	ds_write_b32 v76, v26 offset:2560
	v_pk_fma_f32 v[8:9], v[118:119], v[0:1], v[12:13] op_sel_hi:[0,1,1]
	v_pk_fma_f32 v[10:11], v[118:119], v[0:1], v[14:15] op_sel:[1,0,0]
	v_pk_fma_f32 v[20:21], v[120:121], v[0:1], v[16:17] op_sel_hi:[0,1,1]
	v_pk_fma_f32 v[22:23], v[120:121], v[0:1], v[18:19] op_sel:[1,0,0]
	v_pk_mul_f32 v[4:5], v[8:9], v[122:123] op_sel_hi:[1,0]
	v_pk_mul_f32 v[6:7], v[10:11], v[122:123] op_sel:[0,1]
	v_pk_fma_f32 v[4:5], v[20:21], v[124:125], v[4:5] op_sel_hi:[1,0,1]
	v_pk_fma_f32 v[6:7], v[22:23], v[124:125], v[6:7] op_sel:[0,1,0]
	ds_read_b128 v[106:109], v74 offset:30464
	ds_read_b128 v[110:113], v74 offset:14080
	ds_read_b128 v[114:117], v74 offset:22272
	ds_read_b128 v[118:121], v74 offset:38656
	ds_read_b128 v[122:125], v74 offset:5888
	ds_read_b64 v[126:127], v75 offset:43904
	s_waitcnt lgkmcnt(7)
; __device__ __forceinline__ void rwkv_scan_phase(Frame& F, const bf16* RKV, const float* WAG, const bf16* AGB, const float* k_k, const float* k_a, const float* r_k, bf16* Y, float* BS, float* ST2) {
;     ...
;                 f32x2 r0[4], w0[4], k0[4], a0[4], b0[4], r1[4], w1[4], k1[4], a1[4], b1[4]; float v0, v1;
;                 SC_LOAD(r0, w0, k0, a0, b0, v0, 0);
; #pragma unroll
;                 for (int t = 0; t < SC_T; t += 2) {
;                     SC_LOAD(r1, w1, k1, a1, b1, v1, t + 1);
;                     SC_STEP(r0, w0, k0, a0, b0, v0, t);
;                     if (t + 2 < SC_T) SC_LOAD(r0, w0, k0, a0, b0, v0, t + 2);
;                     SC_STEP(r1, w1, k1, a1, b1, v1, t + 1);
;                 }
	v_pk_mul_f32 v[0:1], v[8:9], v[28:29] op_sel_hi:[1,0]
	v_pk_mul_f32 v[2:3], v[10:11], v[28:29] op_sel:[0,1]
	v_pk_fma_f32 v[0:1], v[20:21], v[30:31], v[0:1] op_sel_hi:[1,0,1]
	v_pk_fma_f32 v[2:3], v[22:23], v[30:31], v[2:3] op_sel:[0,1,0]
	v_pk_add_f32 v[4:5], v[4:5], v[6:7]
	v_pk_mul_f32 v[12:13], v[8:9], v[32:33] op_sel_hi:[1,0]
	v_pk_add_f32 v[0:1], v[0:1], v[2:3]
	v_pk_mul_f32 v[14:15], v[10:11], v[32:33] op_sel:[0,1]
	v_cndmask_b32_e32 v24, v4, v5, vcc
	v_cndmask_b32_e32 v25, v5, v4, vcc
	v_pk_mul_f32 v[16:17], v[20:21], v[34:35] op_sel_hi:[1,0]
	v_pk_mul_f32 v[18:19], v[22:23], v[34:35] op_sel:[0,1]
	v_add_f32_dpp v0, v0, v0 quad_perm:[1,0,3,2] row_mask:0xf bank_mask:0xf bound_ctrl:1
	v_add_f32_dpp v1, v1, v1 quad_perm:[1,0,3,2] row_mask:0xf bank_mask:0xf bound_ctrl:1
	v_add_f32_dpp v26, v25, v24 quad_perm:[1,0,3,2] row_mask:0xf bank_mask:0xf bound_ctrl:1
	v_pk_fma_f32 v[12:13], v[36:37], v[48:49], v[12:13] op_sel_hi:[0,1,1]
	v_pk_fma_f32 v[14:15], v[36:37], v[48:49], v[14:15] op_sel:[1,0,0]
	v_add_f32_dpp v0, v0, v0 quad_perm:[2,3,0,1] row_mask:0xf bank_mask:0xf bound_ctrl:1
	v_add_f32_dpp v1, v1, v1 quad_perm:[2,3,0,1] row_mask:0xf bank_mask:0xf bound_ctrl:1
	v_add_f32_dpp v26, v26, v26 quad_perm:[2,3,0,1] row_mask:0xf bank_mask:0xf bound_ctrl:1
	v_pk_fma_f32 v[16:17], v[38:39], v[48:49], v[16:17] op_sel_hi:[0,1,1]
	v_pk_fma_f32 v[18:19], v[38:39], v[48:49], v[18:19] op_sel:[1,0,0]
	v_add_f32_dpp v0, v0, v0 row_half_mirror row_mask:0xf bank_mask:0xf bound_ctrl:1
	v_add_f32_dpp v1, v1, v1 row_half_mirror row_mask:0xf bank_mask:0xf bound_ctrl:1
	v_add_f32_dpp v26, v26, v26 row_ror:4 row_mask:0xf bank_mask:0xf bound_ctrl:1
	s_nop 0
	v_add_f32_dpp v0, v0, v0 row_mirror row_mask:0xf bank_mask:0xf bound_ctrl:1
	v_add_f32_dpp v1, v1, v1 row_mirror row_mask:0xf bank_mask:0xf bound_ctrl:1
	v_add_f32_dpp v26, v26, v26 row_ror:8 row_mask:0xf bank_mask:0xf bound_ctrl:1
	ds_write_b32 v76, v26 offset:2688
	v_pk_fma_f32 v[8:9], v[40:41], v[0:1], v[12:13] op_sel_hi:[0,1,1]
	v_pk_fma_f32 v[10:11], v[40:41], v[0:1], v[14:15] op_sel:[1,0,0]
	v_pk_fma_f32 v[20:21], v[42:43], v[0:1], v[16:17] op_sel_hi:[0,1,1]
	v_pk_fma_f32 v[22:23], v[42:43], v[0:1], v[18:19] op_sel:[1,0,0]
	v_pk_mul_f32 v[4:5], v[8:9], v[44:45] op_sel_hi:[1,0]
	v_pk_mul_f32 v[6:7], v[10:11], v[44:45] op_sel:[0,1]
	v_pk_fma_f32 v[4:5], v[20:21], v[46:47], v[4:5] op_sel_hi:[1,0,1]
	v_pk_fma_f32 v[6:7], v[22:23], v[46:47], v[6:7] op_sel:[0,1,0]
	ds_read_b128 v[28:31], v74 offset:30720
	ds_read_b128 v[32:35], v74 offset:14336
	ds_read_b128 v[36:39], v74 offset:22528
	ds_read_b128 v[40:43], v74 offset:38912
	ds_read_b128 v[44:47], v74 offset:6144
	ds_read_b64 v[48:49], v75 offset:44032
	s_waitcnt lgkmcnt(7)
	v_pk_mul_f32 v[0:1], v[8:9], v[106:107] op_sel_hi:[1,0]
	v_pk_mul_f32 v[2:3], v[10:11], v[106:107] op_sel:[0,1]
	v_pk_fma_f32 v[0:1], v[20:21], v[108:109], v[0:1] op_sel_hi:[1,0,1]
	v_pk_fma_f32 v[2:3], v[22:23], v[108:109], v[2:3] op_sel:[0,1,0]
	v_pk_add_f32 v[4:5], v[4:5], v[6:7]
	v_pk_mul_f32 v[12:13], v[8:9], v[110:111] op_sel_hi:[1,0]
	v_pk_add_f32 v[0:1], v[0:1], v[2:3]
	v_pk_mul_f32 v[14:15], v[10:11], v[110:111] op_sel:[0,1]
	v_cndmask_b32_e32 v24, v4, v5, vcc
	v_cndmask_b32_e32 v25, v5, v4, vcc
	v_pk_mul_f32 v[16:17], v[20:21], v[112:113] op_sel_hi:[1,0]
	v_pk_mul_f32 v[18:19], v[22:23], v[112:113] op_sel:[0,1]
	v_add_f32_dpp v0, v0, v0 quad_perm:[1,0,3,2] row_mask:0xf bank_mask:0xf bound_ctrl:1
	v_add_f32_dpp v1, v1, v1 quad_perm:[1,0,3,2] row_mask:0xf bank_mask:0xf bound_ctrl:1
	v_add_f32_dpp v26, v25, v24 quad_perm:[1,0,3,2] row_mask:0xf bank_mask:0xf bound_ctrl:1
	v_pk_fma_f32 v[12:13], v[114:115], v[126:127], v[12:13] op_sel_hi:[0,1,1]
	v_pk_fma_f32 v[14:15], v[114:115], v[126:127], v[14:15] op_sel:[1,0,0]
	v_add_f32_dpp v0, v0, v0 quad_perm:[2,3,0,1] row_mask:0xf bank_mask:0xf bound_ctrl:1
	v_add_f32_dpp v1, v1, v1 quad_perm:[2,3,0,1] row_mask:0xf bank_mask:0xf bound_ctrl:1
	v_add_f32_dpp v26, v26, v26 quad_perm:[2,3,0,1] row_mask:0xf bank_mask:0xf bound_ctrl:1
	v_pk_fma_f32 v[16:17], v[116:117], v[126:127], v[16:17] op_sel_hi:[0,1,1]
	v_pk_fma_f32 v[18:19], v[116:117], v[126:127], v[18:19] op_sel:[1,0,0]
	v_add_f32_dpp v0, v0, v0 row_half_mirror row_mask:0xf bank_mask:0xf bound_ctrl:1
	v_add_f32_dpp v1, v1, v1 row_half_mirror row_mask:0xf bank_mask:0xf bound_ctrl:1
	v_add_f32_dpp v26, v26, v26 row_ror:4 row_mask:0xf bank_mask:0xf bound_ctrl:1
	s_nop 0
	v_add_f32_dpp v0, v0, v0 row_mirror row_mask:0xf bank_mask:0xf bound_ctrl:1
	v_add_f32_dpp v1, v1, v1 row_mirror row_mask:0xf bank_mask:0xf bound_ctrl:1
	v_add_f32_dpp v26, v26, v26 row_ror:8 row_mask:0xf bank_mask:0xf bound_ctrl:1
	ds_write_b32 v76, v26 offset:2816
	v_pk_fma_f32 v[8:9], v[118:119], v[0:1], v[12:13] op_sel_hi:[0,1,1]
	v_pk_fma_f32 v[10:11], v[118:119], v[0:1], v[14:15] op_sel:[1,0,0]
	v_pk_fma_f32 v[20:21], v[120:121], v[0:1], v[16:17] op_sel_hi:[0,1,1]
	v_pk_fma_f32 v[22:23], v[120:121], v[0:1], v[18:19] op_sel:[1,0,0]
	v_pk_mul_f32 v[4:5], v[8:9], v[122:123] op_sel_hi:[1,0]
	v_pk_mul_f32 v[6:7], v[10:11], v[122:123] op_sel:[0,1]
	v_pk_fma_f32 v[4:5], v[20:21], v[124:125], v[4:5] op_sel_hi:[1,0,1]
	v_pk_fma_f32 v[6:7], v[22:23], v[124:125], v[6:7] op_sel:[0,1,0]
	ds_read_b128 v[106:109], v74 offset:30976
	ds_read_b128 v[110:113], v74 offset:14592
	ds_read_b128 v[114:117], v74 offset:22784
	ds_read_b128 v[118:121], v74 offset:39168
	ds_read_b128 v[122:125], v74 offset:6400
	ds_read_b64 v[126:127], v75 offset:44160
	s_waitcnt lgkmcnt(7)
; __device__ __forceinline__ void rwkv_scan_phase(Frame& F, const bf16* RKV, const float* WAG, const bf16* AGB, const float* k_k, const float* k_a, const float* r_k, bf16* Y, float* BS, float* ST2) {
;     ...
;                 f32x2 r0[4], w0[4], k0[4], a0[4], b0[4], r1[4], w1[4], k1[4], a1[4], b1[4]; float v0, v1;
;                 SC_LOAD(r0, w0, k0, a0, b0, v0, 0);
; #pragma unroll
;                 for (int t = 0; t < SC_T; t += 2) {
;                     SC_LOAD(r1, w1, k1, a1, b1, v1, t + 1);
;                     SC_STEP(r0, w0, k0, a0, b0, v0, t);
;                     if (t + 2 < SC_T) SC_LOAD(r0, w0, k0, a0, b0, v0, t + 2);
;                     SC_STEP(r1, w1, k1, a1, b1, v1, t + 1);
;                 }
	v_pk_mul_f32 v[0:1], v[8:9], v[28:29] op_sel_hi:[1,0]
	v_pk_mul_f32 v[2:3], v[10:11], v[28:29] op_sel:[0,1]
	v_pk_fma_f32 v[0:1], v[20:21], v[30:31], v[0:1] op_sel_hi:[1,0,1]
	v_pk_fma_f32 v[2:3], v[22:23], v[30:31], v[2:3] op_sel:[0,1,0]
	v_pk_add_f32 v[4:5], v[4:5], v[6:7]
	v_pk_mul_f32 v[12:13], v[8:9], v[32:33] op_sel_hi:[1,0]
	v_pk_add_f32 v[0:1], v[0:1], v[2:3]
	v_pk_mul_f32 v[14:15], v[10:11], v[32:33] op_sel:[0,1]
	v_cndmask_b32_e32 v24, v4, v5, vcc
	v_cndmask_b32_e32 v25, v5, v4, vcc
	v_pk_mul_f32 v[16:17], v[20:21], v[34:35] op_sel_hi:[1,0]
	v_pk_mul_f32 v[18:19], v[22:23], v[34:35] op_sel:[0,1]
	v_add_f32_dpp v0, v0, v0 quad_perm:[1,0,3,2] row_mask:0xf bank_mask:0xf bound_ctrl:1
	v_add_f32_dpp v1, v1, v1 quad_perm:[1,0,3,2] row_mask:0xf bank_mask:0xf bound_ctrl:1
	v_add_f32_dpp v26, v25, v24 quad_perm:[1,0,3,2] row_mask:0xf bank_mask:0xf bound_ctrl:1
	v_pk_fma_f32 v[12:13], v[36:37], v[48:49], v[12:13] op_sel_hi:[0,1,1]
	v_pk_fma_f32 v[14:15], v[36:37], v[48:49], v[14:15] op_sel:[1,0,0]
	v_add_f32_dpp v0, v0, v0 quad_perm:[2,3,0,1] row_mask:0xf bank_mask:0xf bound_ctrl:1
	v_add_f32_dpp v1, v1, v1 quad_perm:[2,3,0,1] row_mask:0xf bank_mask:0xf bound_ctrl:1
	v_add_f32_dpp v26, v26, v26 quad_perm:[2,3,0,1] row_mask:0xf bank_mask:0xf bound_ctrl:1
	v_pk_fma_f32 v[16:17], v[38:39], v[48:49], v[16:17] op_sel_hi:[0,1,1]
	v_pk_fma_f32 v[18:19], v[38:39], v[48:49], v[18:19] op_sel:[1,0,0]
	v_add_f32_dpp v0, v0, v0 row_half_mirror row_mask:0xf bank_mask:0xf bound_ctrl:1
	v_add_f32_dpp v1, v1, v1 row_half_mirror row_mask:0xf bank_mask:0xf bound_ctrl:1
	v_add_f32_dpp v26, v26, v26 row_ror:4 row_mask:0xf bank_mask:0xf bound_ctrl:1
	s_nop 0
	v_add_f32_dpp v0, v0, v0 row_mirror row_mask:0xf bank_mask:0xf bound_ctrl:1
	v_add_f32_dpp v1, v1, v1 row_mirror row_mask:0xf bank_mask:0xf bound_ctrl:1
	v_add_f32_dpp v26, v26, v26 row_ror:8 row_mask:0xf bank_mask:0xf bound_ctrl:1
	ds_write_b32 v76, v26 offset:2944
	v_pk_fma_f32 v[8:9], v[40:41], v[0:1], v[12:13] op_sel_hi:[0,1,1]
	v_pk_fma_f32 v[10:11], v[40:41], v[0:1], v[14:15] op_sel:[1,0,0]
	v_pk_fma_f32 v[20:21], v[42:43], v[0:1], v[16:17] op_sel_hi:[0,1,1]
	v_pk_fma_f32 v[22:23], v[42:43], v[0:1], v[18:19] op_sel:[1,0,0]
	v_pk_mul_f32 v[4:5], v[8:9], v[44:45] op_sel_hi:[1,0]
	v_pk_mul_f32 v[6:7], v[10:11], v[44:45] op_sel:[0,1]
	v_pk_fma_f32 v[4:5], v[20:21], v[46:47], v[4:5] op_sel_hi:[1,0,1]
	v_pk_fma_f32 v[6:7], v[22:23], v[46:47], v[6:7] op_sel:[0,1,0]
	ds_read_b128 v[28:31], v74 offset:31232
	ds_read_b128 v[32:35], v74 offset:14848
	ds_read_b128 v[36:39], v74 offset:23040
	ds_read_b128 v[40:43], v74 offset:39424
	ds_read_b128 v[44:47], v74 offset:6656
	ds_read_b64 v[48:49], v75 offset:44288
	s_waitcnt lgkmcnt(7)
	v_pk_mul_f32 v[0:1], v[8:9], v[106:107] op_sel_hi:[1,0]
	v_pk_mul_f32 v[2:3], v[10:11], v[106:107] op_sel:[0,1]
	v_pk_fma_f32 v[0:1], v[20:21], v[108:109], v[0:1] op_sel_hi:[1,0,1]
	v_pk_fma_f32 v[2:3], v[22:23], v[108:109], v[2:3] op_sel:[0,1,0]
	v_pk_add_f32 v[4:5], v[4:5], v[6:7]
	v_pk_mul_f32 v[12:13], v[8:9], v[110:111] op_sel_hi:[1,0]
	v_pk_add_f32 v[0:1], v[0:1], v[2:3]
	v_pk_mul_f32 v[14:15], v[10:11], v[110:111] op_sel:[0,1]
	v_cndmask_b32_e32 v24, v4, v5, vcc
	v_cndmask_b32_e32 v25, v5, v4, vcc
	v_pk_mul_f32 v[16:17], v[20:21], v[112:113] op_sel_hi:[1,0]
	v_pk_mul_f32 v[18:19], v[22:23], v[112:113] op_sel:[0,1]
	v_add_f32_dpp v0, v0, v0 quad_perm:[1,0,3,2] row_mask:0xf bank_mask:0xf bound_ctrl:1
	v_add_f32_dpp v1, v1, v1 quad_perm:[1,0,3,2] row_mask:0xf bank_mask:0xf bound_ctrl:1
	v_add_f32_dpp v26, v25, v24 quad_perm:[1,0,3,2] row_mask:0xf bank_mask:0xf bound_ctrl:1
	v_pk_fma_f32 v[12:13], v[114:115], v[126:127], v[12:13] op_sel_hi:[0,1,1]
	v_pk_fma_f32 v[14:15], v[114:115], v[126:127], v[14:15] op_sel:[1,0,0]
	v_add_f32_dpp v0, v0, v0 quad_perm:[2,3,0,1] row_mask:0xf bank_mask:0xf bound_ctrl:1
	v_add_f32_dpp v1, v1, v1 quad_perm:[2,3,0,1] row_mask:0xf bank_mask:0xf bound_ctrl:1
	v_add_f32_dpp v26, v26, v26 quad_perm:[2,3,0,1] row_mask:0xf bank_mask:0xf bound_ctrl:1
	v_pk_fma_f32 v[16:17], v[116:117], v[126:127], v[16:17] op_sel_hi:[0,1,1]
	v_pk_fma_f32 v[18:19], v[116:117], v[126:127], v[18:19] op_sel:[1,0,0]
	v_add_f32_dpp v0, v0, v0 row_half_mirror row_mask:0xf bank_mask:0xf bound_ctrl:1
	v_add_f32_dpp v1, v1, v1 row_half_mirror row_mask:0xf bank_mask:0xf bound_ctrl:1
	v_add_f32_dpp v26, v26, v26 row_ror:4 row_mask:0xf bank_mask:0xf bound_ctrl:1
	s_nop 0
	v_add_f32_dpp v0, v0, v0 row_mirror row_mask:0xf bank_mask:0xf bound_ctrl:1
	v_add_f32_dpp v1, v1, v1 row_mirror row_mask:0xf bank_mask:0xf bound_ctrl:1
	v_add_f32_dpp v26, v26, v26 row_ror:8 row_mask:0xf bank_mask:0xf bound_ctrl:1
	ds_write_b32 v76, v26 offset:3072
	v_pk_fma_f32 v[8:9], v[118:119], v[0:1], v[12:13] op_sel_hi:[0,1,1]
	v_pk_fma_f32 v[10:11], v[118:119], v[0:1], v[14:15] op_sel:[1,0,0]
	v_pk_fma_f32 v[20:21], v[120:121], v[0:1], v[16:17] op_sel_hi:[0,1,1]
	v_pk_fma_f32 v[22:23], v[120:121], v[0:1], v[18:19] op_sel:[1,0,0]
	v_pk_mul_f32 v[4:5], v[8:9], v[122:123] op_sel_hi:[1,0]
	v_pk_mul_f32 v[6:7], v[10:11], v[122:123] op_sel:[0,1]
	v_pk_fma_f32 v[4:5], v[20:21], v[124:125], v[4:5] op_sel_hi:[1,0,1]
	v_pk_fma_f32 v[6:7], v[22:23], v[124:125], v[6:7] op_sel:[0,1,0]
	ds_read_b128 v[106:109], v74 offset:31488
	ds_read_b128 v[110:113], v74 offset:15104
	ds_read_b128 v[114:117], v74 offset:23296
	ds_read_b128 v[118:121], v74 offset:39680
	ds_read_b128 v[122:125], v74 offset:6912
	ds_read_b64 v[126:127], v75 offset:44416
	s_waitcnt lgkmcnt(7)
; __device__ __forceinline__ void rwkv_scan_phase(Frame& F, const bf16* RKV, const float* WAG, const bf16* AGB, const float* k_k, const float* k_a, const float* r_k, bf16* Y, float* BS, float* ST2) {
;     ...
;                 f32x2 r0[4], w0[4], k0[4], a0[4], b0[4], r1[4], w1[4], k1[4], a1[4], b1[4]; float v0, v1;
;                 SC_LOAD(r0, w0, k0, a0, b0, v0, 0);
; #pragma unroll
;                 for (int t = 0; t < SC_T; t += 2) {
;                     SC_LOAD(r1, w1, k1, a1, b1, v1, t + 1);
;                     SC_STEP(r0, w0, k0, a0, b0, v0, t);
;                     if (t + 2 < SC_T) SC_LOAD(r0, w0, k0, a0, b0, v0, t + 2);
;                     SC_STEP(r1, w1, k1, a1, b1, v1, t + 1);
;                 }
	v_pk_mul_f32 v[0:1], v[8:9], v[28:29] op_sel_hi:[1,0]
	v_pk_mul_f32 v[2:3], v[10:11], v[28:29] op_sel:[0,1]
	v_pk_fma_f32 v[0:1], v[20:21], v[30:31], v[0:1] op_sel_hi:[1,0,1]
	v_pk_fma_f32 v[2:3], v[22:23], v[30:31], v[2:3] op_sel:[0,1,0]
	v_pk_add_f32 v[4:5], v[4:5], v[6:7]
	v_pk_mul_f32 v[12:13], v[8:9], v[32:33] op_sel_hi:[1,0]
	v_pk_add_f32 v[0:1], v[0:1], v[2:3]
	v_pk_mul_f32 v[14:15], v[10:11], v[32:33] op_sel:[0,1]
	v_cndmask_b32_e32 v24, v4, v5, vcc
	v_cndmask_b32_e32 v25, v5, v4, vcc
	v_pk_mul_f32 v[16:17], v[20:21], v[34:35] op_sel_hi:[1,0]
	v_pk_mul_f32 v[18:19], v[22:23], v[34:35] op_sel:[0,1]
	v_add_f32_dpp v0, v0, v0 quad_perm:[1,0,3,2] row_mask:0xf bank_mask:0xf bound_ctrl:1
	v_add_f32_dpp v1, v1, v1 quad_perm:[1,0,3,2] row_mask:0xf bank_mask:0xf bound_ctrl:1
	v_add_f32_dpp v26, v25, v24 quad_perm:[1,0,3,2] row_mask:0xf bank_mask:0xf bound_ctrl:1
	v_pk_fma_f32 v[12:13], v[36:37], v[48:49], v[12:13] op_sel_hi:[0,1,1]
	v_pk_fma_f32 v[14:15], v[36:37], v[48:49], v[14:15] op_sel:[1,0,0]
	v_add_f32_dpp v0, v0, v0 quad_perm:[2,3,0,1] row_mask:0xf bank_mask:0xf bound_ctrl:1
	v_add_f32_dpp v1, v1, v1 quad_perm:[2,3,0,1] row_mask:0xf bank_mask:0xf bound_ctrl:1
	v_add_f32_dpp v26, v26, v26 quad_perm:[2,3,0,1] row_mask:0xf bank_mask:0xf bound_ctrl:1
	v_pk_fma_f32 v[16:17], v[38:39], v[48:49], v[16:17] op_sel_hi:[0,1,1]
	v_pk_fma_f32 v[18:19], v[38:39], v[48:49], v[18:19] op_sel:[1,0,0]
	v_add_f32_dpp v0, v0, v0 row_half_mirror row_mask:0xf bank_mask:0xf bound_ctrl:1
	v_add_f32_dpp v1, v1, v1 row_half_mirror row_mask:0xf bank_mask:0xf bound_ctrl:1
	v_add_f32_dpp v26, v26, v26 row_ror:4 row_mask:0xf bank_mask:0xf bound_ctrl:1
	s_nop 0
	v_add_f32_dpp v0, v0, v0 row_mirror row_mask:0xf bank_mask:0xf bound_ctrl:1
	v_add_f32_dpp v1, v1, v1 row_mirror row_mask:0xf bank_mask:0xf bound_ctrl:1
	v_add_f32_dpp v26, v26, v26 row_ror:8 row_mask:0xf bank_mask:0xf bound_ctrl:1
	ds_write_b32 v76, v26 offset:3200
	v_pk_fma_f32 v[8:9], v[40:41], v[0:1], v[12:13] op_sel_hi:[0,1,1]
	v_pk_fma_f32 v[10:11], v[40:41], v[0:1], v[14:15] op_sel:[1,0,0]
	v_pk_fma_f32 v[20:21], v[42:43], v[0:1], v[16:17] op_sel_hi:[0,1,1]
	v_pk_fma_f32 v[22:23], v[42:43], v[0:1], v[18:19] op_sel:[1,0,0]
	v_pk_mul_f32 v[4:5], v[8:9], v[44:45] op_sel_hi:[1,0]
	v_pk_mul_f32 v[6:7], v[10:11], v[44:45] op_sel:[0,1]
	v_pk_fma_f32 v[4:5], v[20:21], v[46:47], v[4:5] op_sel_hi:[1,0,1]
	v_pk_fma_f32 v[6:7], v[22:23], v[46:47], v[6:7] op_sel:[0,1,0]
	ds_read_b128 v[28:31], v74 offset:31744
	ds_read_b128 v[32:35], v74 offset:15360
	ds_read_b128 v[36:39], v74 offset:23552
	ds_read_b128 v[40:43], v74 offset:39936
	ds_read_b128 v[44:47], v74 offset:7168
	ds_read_b64 v[48:49], v75 offset:44544
	s_waitcnt lgkmcnt(7)
	v_pk_mul_f32 v[0:1], v[8:9], v[106:107] op_sel_hi:[1,0]
	v_pk_mul_f32 v[2:3], v[10:11], v[106:107] op_sel:[0,1]
	v_pk_fma_f32 v[0:1], v[20:21], v[108:109], v[0:1] op_sel_hi:[1,0,1]
	v_pk_fma_f32 v[2:3], v[22:23], v[108:109], v[2:3] op_sel:[0,1,0]
	v_pk_add_f32 v[4:5], v[4:5], v[6:7]
	v_pk_mul_f32 v[12:13], v[8:9], v[110:111] op_sel_hi:[1,0]
	v_pk_add_f32 v[0:1], v[0:1], v[2:3]
	v_pk_mul_f32 v[14:15], v[10:11], v[110:111] op_sel:[0,1]
	v_cndmask_b32_e32 v24, v4, v5, vcc
	v_cndmask_b32_e32 v25, v5, v4, vcc
	v_pk_mul_f32 v[16:17], v[20:21], v[112:113] op_sel_hi:[1,0]
	v_pk_mul_f32 v[18:19], v[22:23], v[112:113] op_sel:[0,1]
	v_add_f32_dpp v0, v0, v0 quad_perm:[1,0,3,2] row_mask:0xf bank_mask:0xf bound_ctrl:1
	v_add_f32_dpp v1, v1, v1 quad_perm:[1,0,3,2] row_mask:0xf bank_mask:0xf bound_ctrl:1
	v_add_f32_dpp v26, v25, v24 quad_perm:[1,0,3,2] row_mask:0xf bank_mask:0xf bound_ctrl:1
	v_pk_fma_f32 v[12:13], v[114:115], v[126:127], v[12:13] op_sel_hi:[0,1,1]
	v_pk_fma_f32 v[14:15], v[114:115], v[126:127], v[14:15] op_sel:[1,0,0]
	v_add_f32_dpp v0, v0, v0 quad_perm:[2,3,0,1] row_mask:0xf bank_mask:0xf bound_ctrl:1
	v_add_f32_dpp v1, v1, v1 quad_perm:[2,3,0,1] row_mask:0xf bank_mask:0xf bound_ctrl:1
	v_add_f32_dpp v26, v26, v26 quad_perm:[2,3,0,1] row_mask:0xf bank_mask:0xf bound_ctrl:1
	v_pk_fma_f32 v[16:17], v[116:117], v[126:127], v[16:17] op_sel_hi:[0,1,1]
	v_pk_fma_f32 v[18:19], v[116:117], v[126:127], v[18:19] op_sel:[1,0,0]
	v_add_f32_dpp v0, v0, v0 row_half_mirror row_mask:0xf bank_mask:0xf bound_ctrl:1
	v_add_f32_dpp v1, v1, v1 row_half_mirror row_mask:0xf bank_mask:0xf bound_ctrl:1
	v_add_f32_dpp v26, v26, v26 row_ror:4 row_mask:0xf bank_mask:0xf bound_ctrl:1
	s_nop 0
	v_add_f32_dpp v0, v0, v0 row_mirror row_mask:0xf bank_mask:0xf bound_ctrl:1
	v_add_f32_dpp v1, v1, v1 row_mirror row_mask:0xf bank_mask:0xf bound_ctrl:1
	v_add_f32_dpp v26, v26, v26 row_ror:8 row_mask:0xf bank_mask:0xf bound_ctrl:1
	ds_write_b32 v76, v26 offset:3328
	v_pk_fma_f32 v[8:9], v[118:119], v[0:1], v[12:13] op_sel_hi:[0,1,1]
	v_pk_fma_f32 v[10:11], v[118:119], v[0:1], v[14:15] op_sel:[1,0,0]
	v_pk_fma_f32 v[20:21], v[120:121], v[0:1], v[16:17] op_sel_hi:[0,1,1]
	v_pk_fma_f32 v[22:23], v[120:121], v[0:1], v[18:19] op_sel:[1,0,0]
	v_pk_mul_f32 v[4:5], v[8:9], v[122:123] op_sel_hi:[1,0]
	v_pk_mul_f32 v[6:7], v[10:11], v[122:123] op_sel:[0,1]
	v_pk_fma_f32 v[4:5], v[20:21], v[124:125], v[4:5] op_sel_hi:[1,0,1]
	v_pk_fma_f32 v[6:7], v[22:23], v[124:125], v[6:7] op_sel:[0,1,0]
	ds_read_b128 v[106:109], v74 offset:32000
	ds_read_b128 v[110:113], v74 offset:15616
	ds_read_b128 v[114:117], v74 offset:23808
	ds_read_b128 v[118:121], v74 offset:40192
	ds_read_b128 v[122:125], v74 offset:7424
	ds_read_b64 v[126:127], v75 offset:44672
	s_waitcnt lgkmcnt(7)
; __device__ __forceinline__ void rwkv_scan_phase(Frame& F, const bf16* RKV, const float* WAG, const bf16* AGB, const float* k_k, const float* k_a, const float* r_k, bf16* Y, float* BS, float* ST2) {
;     ...
;                 f32x2 r0[4], w0[4], k0[4], a0[4], b0[4], r1[4], w1[4], k1[4], a1[4], b1[4]; float v0, v1;
;                 SC_LOAD(r0, w0, k0, a0, b0, v0, 0);
; #pragma unroll
;                 for (int t = 0; t < SC_T; t += 2) {
;                     SC_LOAD(r1, w1, k1, a1, b1, v1, t + 1);
;                     SC_STEP(r0, w0, k0, a0, b0, v0, t);
;                     if (t + 2 < SC_T) SC_LOAD(r0, w0, k0, a0, b0, v0, t + 2);
;                     SC_STEP(r1, w1, k1, a1, b1, v1, t + 1);
;                 }
	v_pk_mul_f32 v[0:1], v[8:9], v[28:29] op_sel_hi:[1,0]
	v_pk_mul_f32 v[2:3], v[10:11], v[28:29] op_sel:[0,1]
	v_pk_fma_f32 v[0:1], v[20:21], v[30:31], v[0:1] op_sel_hi:[1,0,1]
	v_pk_fma_f32 v[2:3], v[22:23], v[30:31], v[2:3] op_sel:[0,1,0]
	v_pk_add_f32 v[4:5], v[4:5], v[6:7]
	v_pk_mul_f32 v[12:13], v[8:9], v[32:33] op_sel_hi:[1,0]
	v_pk_add_f32 v[0:1], v[0:1], v[2:3]
	v_pk_mul_f32 v[14:15], v[10:11], v[32:33] op_sel:[0,1]
	v_cndmask_b32_e32 v24, v4, v5, vcc
	v_cndmask_b32_e32 v25, v5, v4, vcc
	v_pk_mul_f32 v[16:17], v[20:21], v[34:35] op_sel_hi:[1,0]
	v_pk_mul_f32 v[18:19], v[22:23], v[34:35] op_sel:[0,1]
	v_add_f32_dpp v0, v0, v0 quad_perm:[1,0,3,2] row_mask:0xf bank_mask:0xf bound_ctrl:1
	v_add_f32_dpp v1, v1, v1 quad_perm:[1,0,3,2] row_mask:0xf bank_mask:0xf bound_ctrl:1
	v_add_f32_dpp v26, v25, v24 quad_perm:[1,0,3,2] row_mask:0xf bank_mask:0xf bound_ctrl:1
	v_pk_fma_f32 v[12:13], v[36:37], v[48:49], v[12:13] op_sel_hi:[0,1,1]
	v_pk_fma_f32 v[14:15], v[36:37], v[48:49], v[14:15] op_sel:[1,0,0]
	v_add_f32_dpp v0, v0, v0 quad_perm:[2,3,0,1] row_mask:0xf bank_mask:0xf bound_ctrl:1
	v_add_f32_dpp v1, v1, v1 quad_perm:[2,3,0,1] row_mask:0xf bank_mask:0xf bound_ctrl:1
	v_add_f32_dpp v26, v26, v26 quad_perm:[2,3,0,1] row_mask:0xf bank_mask:0xf bound_ctrl:1
	v_pk_fma_f32 v[16:17], v[38:39], v[48:49], v[16:17] op_sel_hi:[0,1,1]
	v_pk_fma_f32 v[18:19], v[38:39], v[48:49], v[18:19] op_sel:[1,0,0]
	v_add_f32_dpp v0, v0, v0 row_half_mirror row_mask:0xf bank_mask:0xf bound_ctrl:1
	v_add_f32_dpp v1, v1, v1 row_half_mirror row_mask:0xf bank_mask:0xf bound_ctrl:1
	v_add_f32_dpp v26, v26, v26 row_ror:4 row_mask:0xf bank_mask:0xf bound_ctrl:1
	s_nop 0
	v_add_f32_dpp v0, v0, v0 row_mirror row_mask:0xf bank_mask:0xf bound_ctrl:1
	v_add_f32_dpp v1, v1, v1 row_mirror row_mask:0xf bank_mask:0xf bound_ctrl:1
	v_add_f32_dpp v26, v26, v26 row_ror:8 row_mask:0xf bank_mask:0xf bound_ctrl:1
	ds_write_b32 v76, v26 offset:3456
	v_pk_fma_f32 v[8:9], v[40:41], v[0:1], v[12:13] op_sel_hi:[0,1,1]
	v_pk_fma_f32 v[10:11], v[40:41], v[0:1], v[14:15] op_sel:[1,0,0]
	v_pk_fma_f32 v[20:21], v[42:43], v[0:1], v[16:17] op_sel_hi:[0,1,1]
	v_pk_fma_f32 v[22:23], v[42:43], v[0:1], v[18:19] op_sel:[1,0,0]
	v_pk_mul_f32 v[4:5], v[8:9], v[44:45] op_sel_hi:[1,0]
	v_pk_mul_f32 v[6:7], v[10:11], v[44:45] op_sel:[0,1]
	v_pk_fma_f32 v[4:5], v[20:21], v[46:47], v[4:5] op_sel_hi:[1,0,1]
	v_pk_fma_f32 v[6:7], v[22:23], v[46:47], v[6:7] op_sel:[0,1,0]
	ds_read_b128 v[28:31], v74 offset:32256
	ds_read_b128 v[32:35], v74 offset:15872
	ds_read_b128 v[36:39], v74 offset:24064
	ds_read_b128 v[40:43], v74 offset:40448
	ds_read_b128 v[44:47], v74 offset:7680
	ds_read_b64 v[48:49], v75 offset:44800
	s_waitcnt lgkmcnt(7)
	v_pk_mul_f32 v[0:1], v[8:9], v[106:107] op_sel_hi:[1,0]
	v_pk_mul_f32 v[2:3], v[10:11], v[106:107] op_sel:[0,1]
	v_pk_fma_f32 v[0:1], v[20:21], v[108:109], v[0:1] op_sel_hi:[1,0,1]
	v_pk_fma_f32 v[2:3], v[22:23], v[108:109], v[2:3] op_sel:[0,1,0]
	v_pk_add_f32 v[4:5], v[4:5], v[6:7]
	v_pk_mul_f32 v[12:13], v[8:9], v[110:111] op_sel_hi:[1,0]
	v_pk_add_f32 v[0:1], v[0:1], v[2:3]
	v_pk_mul_f32 v[14:15], v[10:11], v[110:111] op_sel:[0,1]
	v_cndmask_b32_e32 v24, v4, v5, vcc
	v_cndmask_b32_e32 v25, v5, v4, vcc
	v_pk_mul_f32 v[16:17], v[20:21], v[112:113] op_sel_hi:[1,0]
	v_pk_mul_f32 v[18:19], v[22:23], v[112:113] op_sel:[0,1]
	v_add_f32_dpp v0, v0, v0 quad_perm:[1,0,3,2] row_mask:0xf bank_mask:0xf bound_ctrl:1
	v_add_f32_dpp v1, v1, v1 quad_perm:[1,0,3,2] row_mask:0xf bank_mask:0xf bound_ctrl:1
	v_add_f32_dpp v26, v25, v24 quad_perm:[1,0,3,2] row_mask:0xf bank_mask:0xf bound_ctrl:1
	v_pk_fma_f32 v[12:13], v[114:115], v[126:127], v[12:13] op_sel_hi:[0,1,1]
	v_pk_fma_f32 v[14:15], v[114:115], v[126:127], v[14:15] op_sel:[1,0,0]
	v_add_f32_dpp v0, v0, v0 quad_perm:[2,3,0,1] row_mask:0xf bank_mask:0xf bound_ctrl:1
	v_add_f32_dpp v1, v1, v1 quad_perm:[2,3,0,1] row_mask:0xf bank_mask:0xf bound_ctrl:1
	v_add_f32_dpp v26, v26, v26 quad_perm:[2,3,0,1] row_mask:0xf bank_mask:0xf bound_ctrl:1
	v_pk_fma_f32 v[16:17], v[116:117], v[126:127], v[16:17] op_sel_hi:[0,1,1]
	v_pk_fma_f32 v[18:19], v[116:117], v[126:127], v[18:19] op_sel:[1,0,0]
	v_add_f32_dpp v0, v0, v0 row_half_mirror row_mask:0xf bank_mask:0xf bound_ctrl:1
	v_add_f32_dpp v1, v1, v1 row_half_mirror row_mask:0xf bank_mask:0xf bound_ctrl:1
	v_add_f32_dpp v26, v26, v26 row_ror:4 row_mask:0xf bank_mask:0xf bound_ctrl:1
	s_nop 0
	v_add_f32_dpp v0, v0, v0 row_mirror row_mask:0xf bank_mask:0xf bound_ctrl:1
	v_add_f32_dpp v1, v1, v1 row_mirror row_mask:0xf bank_mask:0xf bound_ctrl:1
	v_add_f32_dpp v26, v26, v26 row_ror:8 row_mask:0xf bank_mask:0xf bound_ctrl:1
	ds_write_b32 v76, v26 offset:3584
	v_pk_fma_f32 v[8:9], v[118:119], v[0:1], v[12:13] op_sel_hi:[0,1,1]
	v_pk_fma_f32 v[10:11], v[118:119], v[0:1], v[14:15] op_sel:[1,0,0]
	v_pk_fma_f32 v[20:21], v[120:121], v[0:1], v[16:17] op_sel_hi:[0,1,1]
	v_pk_fma_f32 v[22:23], v[120:121], v[0:1], v[18:19] op_sel:[1,0,0]
	v_pk_mul_f32 v[4:5], v[8:9], v[122:123] op_sel_hi:[1,0]
	v_pk_mul_f32 v[6:7], v[10:11], v[122:123] op_sel:[0,1]
	v_pk_fma_f32 v[4:5], v[20:21], v[124:125], v[4:5] op_sel_hi:[1,0,1]
	v_pk_fma_f32 v[6:7], v[22:23], v[124:125], v[6:7] op_sel:[0,1,0]
	ds_read_b128 v[106:109], v74 offset:32512
	ds_read_b128 v[110:113], v74 offset:16128
	ds_read_b128 v[114:117], v74 offset:24320
	ds_read_b128 v[118:121], v74 offset:40704
	ds_read_b128 v[122:125], v74 offset:7936
	ds_read_b64 v[126:127], v75 offset:44928
	s_waitcnt lgkmcnt(7)
; #define LAS __attribute__((address_space(3)))
; __device__ __forceinline__ void rwkv_scan_phase(Frame& F, const bf16* RKV, const float* WAG, const bf16* AGB, const float* k_k, const float* k_a, const float* r_k, bf16* Y, float* BS, float* ST2) {
;     ...
;             const int row = lane >> 3, kg = lane & 7, vr = 8 * wave + row;
;             typedef float f32x2 __attribute__((ext_vector_type(2)));
;             f32x2 s[4];
; #pragma unroll
;             for (int i = 0; i < 4; ++i) s[i] = (f32x2){0.f, 0.f};
;             __syncthreads();
;             for (int ci = 0; ci < SEQ / SC_T; ++ci) {
;                 const LAS unsigned char* bp = F.lds + (ci & 1) * SC_BUF; LAS float* yb = (LAS float*)(F.lds + SC_YOFF + (ci & 1) * SC_YB);
;     ...
;                 f32x2 r0[4], w0[4], k0[4], a0[4], b0[4], r1[4], w1[4], k1[4], a1[4], b1[4]; float v0, v1;
;                 SC_LOAD(r0, w0, k0, a0, b0, v0, 0);
; #pragma unroll
;                 for (int t = 0; t < SC_T; t += 2) {
;                     SC_LOAD(r1, w1, k1, a1, b1, v1, t + 1);
;                     SC_STEP(r0, w0, k0, a0, b0, v0, t);
;                     if (t + 2 < SC_T) SC_LOAD(r0, w0, k0, a0, b0, v0, t + 2);
;                     SC_STEP(r1, w1, k1, a1, b1, v1, t + 1);
;                 }
	v_pk_mul_f32 v[0:1], v[8:9], v[28:29] op_sel_hi:[1,0]
	v_pk_mul_f32 v[2:3], v[10:11], v[28:29] op_sel:[0,1]
	v_pk_fma_f32 v[0:1], v[20:21], v[30:31], v[0:1] op_sel_hi:[1,0,1]
	v_pk_fma_f32 v[2:3], v[22:23], v[30:31], v[2:3] op_sel:[0,1,0]
	v_pk_add_f32 v[4:5], v[4:5], v[6:7]
	v_pk_mul_f32 v[12:13], v[8:9], v[32:33] op_sel_hi:[1,0]
	v_pk_add_f32 v[0:1], v[0:1], v[2:3]
	v_pk_mul_f32 v[14:15], v[10:11], v[32:33] op_sel:[0,1]
	v_cndmask_b32_e32 v24, v4, v5, vcc
	v_cndmask_b32_e32 v25, v5, v4, vcc
	v_pk_mul_f32 v[16:17], v[20:21], v[34:35] op_sel_hi:[1,0]
	v_pk_mul_f32 v[18:19], v[22:23], v[34:35] op_sel:[0,1]
	v_add_f32_dpp v0, v0, v0 quad_perm:[1,0,3,2] row_mask:0xf bank_mask:0xf bound_ctrl:1
	v_add_f32_dpp v1, v1, v1 quad_perm:[1,0,3,2] row_mask:0xf bank_mask:0xf bound_ctrl:1
	v_add_f32_dpp v26, v25, v24 quad_perm:[1,0,3,2] row_mask:0xf bank_mask:0xf bound_ctrl:1
	v_pk_fma_f32 v[12:13], v[36:37], v[48:49], v[12:13] op_sel_hi:[0,1,1]
	v_pk_fma_f32 v[14:15], v[36:37], v[48:49], v[14:15] op_sel:[1,0,0]
	v_add_f32_dpp v0, v0, v0 quad_perm:[2,3,0,1] row_mask:0xf bank_mask:0xf bound_ctrl:1
	v_add_f32_dpp v1, v1, v1 quad_perm:[2,3,0,1] row_mask:0xf bank_mask:0xf bound_ctrl:1
	v_add_f32_dpp v26, v26, v26 quad_perm:[2,3,0,1] row_mask:0xf bank_mask:0xf bound_ctrl:1
	v_pk_fma_f32 v[16:17], v[38:39], v[48:49], v[16:17] op_sel_hi:[0,1,1]
	v_pk_fma_f32 v[18:19], v[38:39], v[48:49], v[18:19] op_sel:[1,0,0]
	v_add_f32_dpp v0, v0, v0 row_half_mirror row_mask:0xf bank_mask:0xf bound_ctrl:1
	v_add_f32_dpp v1, v1, v1 row_half_mirror row_mask:0xf bank_mask:0xf bound_ctrl:1
	v_add_f32_dpp v26, v26, v26 row_ror:4 row_mask:0xf bank_mask:0xf bound_ctrl:1
	s_nop 0
	v_add_f32_dpp v0, v0, v0 row_mirror row_mask:0xf bank_mask:0xf bound_ctrl:1
	v_add_f32_dpp v1, v1, v1 row_mirror row_mask:0xf bank_mask:0xf bound_ctrl:1
	v_add_f32_dpp v26, v26, v26 row_ror:8 row_mask:0xf bank_mask:0xf bound_ctrl:1
	ds_write_b32 v76, v26 offset:3712
	v_pk_fma_f32 v[8:9], v[40:41], v[0:1], v[12:13] op_sel_hi:[0,1,1]
	v_pk_fma_f32 v[10:11], v[40:41], v[0:1], v[14:15] op_sel:[1,0,0]
	v_pk_fma_f32 v[20:21], v[42:43], v[0:1], v[16:17] op_sel_hi:[0,1,1]
	v_pk_fma_f32 v[22:23], v[42:43], v[0:1], v[18:19] op_sel:[1,0,0]
	v_pk_mul_f32 v[4:5], v[8:9], v[44:45] op_sel_hi:[1,0]
	v_pk_mul_f32 v[6:7], v[10:11], v[44:45] op_sel:[0,1]
	v_pk_fma_f32 v[4:5], v[20:21], v[46:47], v[4:5] op_sel_hi:[1,0,1]
	v_pk_fma_f32 v[6:7], v[22:23], v[46:47], v[6:7] op_sel:[0,1,0]
	s_waitcnt lgkmcnt(1)
	v_pk_mul_f32 v[0:1], v[8:9], v[106:107] op_sel_hi:[1,0]
	v_pk_mul_f32 v[2:3], v[10:11], v[106:107] op_sel:[0,1]
	v_pk_fma_f32 v[0:1], v[20:21], v[108:109], v[0:1] op_sel_hi:[1,0,1]
	v_pk_fma_f32 v[2:3], v[22:23], v[108:109], v[2:3] op_sel:[0,1,0]
	v_pk_add_f32 v[4:5], v[4:5], v[6:7]
	v_pk_mul_f32 v[12:13], v[8:9], v[110:111] op_sel_hi:[1,0]
	v_pk_add_f32 v[0:1], v[0:1], v[2:3]
	v_pk_mul_f32 v[14:15], v[10:11], v[110:111] op_sel:[0,1]
	v_cndmask_b32_e32 v24, v4, v5, vcc
	v_cndmask_b32_e32 v25, v5, v4, vcc
	v_pk_mul_f32 v[16:17], v[20:21], v[112:113] op_sel_hi:[1,0]
	v_pk_mul_f32 v[18:19], v[22:23], v[112:113] op_sel:[0,1]
	v_add_f32_dpp v0, v0, v0 quad_perm:[1,0,3,2] row_mask:0xf bank_mask:0xf bound_ctrl:1
	v_add_f32_dpp v1, v1, v1 quad_perm:[1,0,3,2] row_mask:0xf bank_mask:0xf bound_ctrl:1
	v_add_f32_dpp v26, v25, v24 quad_perm:[1,0,3,2] row_mask:0xf bank_mask:0xf bound_ctrl:1
	v_pk_fma_f32 v[12:13], v[114:115], v[126:127], v[12:13] op_sel_hi:[0,1,1]
	v_pk_fma_f32 v[14:15], v[114:115], v[126:127], v[14:15] op_sel:[1,0,0]
	v_add_f32_dpp v0, v0, v0 quad_perm:[2,3,0,1] row_mask:0xf bank_mask:0xf bound_ctrl:1
	v_add_f32_dpp v1, v1, v1 quad_perm:[2,3,0,1] row_mask:0xf bank_mask:0xf bound_ctrl:1
	v_add_f32_dpp v26, v26, v26 quad_perm:[2,3,0,1] row_mask:0xf bank_mask:0xf bound_ctrl:1
	v_pk_fma_f32 v[16:17], v[116:117], v[126:127], v[16:17] op_sel_hi:[0,1,1]
	v_pk_fma_f32 v[18:19], v[116:117], v[126:127], v[18:19] op_sel:[1,0,0]
	v_add_f32_dpp v0, v0, v0 row_half_mirror row_mask:0xf bank_mask:0xf bound_ctrl:1
	v_add_f32_dpp v1, v1, v1 row_half_mirror row_mask:0xf bank_mask:0xf bound_ctrl:1
	v_add_f32_dpp v26, v26, v26 row_ror:4 row_mask:0xf bank_mask:0xf bound_ctrl:1
	s_nop 0
	v_add_f32_dpp v0, v0, v0 row_mirror row_mask:0xf bank_mask:0xf bound_ctrl:1
	v_add_f32_dpp v1, v1, v1 row_mirror row_mask:0xf bank_mask:0xf bound_ctrl:1
	v_add_f32_dpp v26, v26, v26 row_ror:8 row_mask:0xf bank_mask:0xf bound_ctrl:1
	ds_write_b32 v76, v26 offset:3840
	v_pk_fma_f32 v[8:9], v[118:119], v[0:1], v[12:13] op_sel_hi:[0,1,1]
	v_pk_fma_f32 v[10:11], v[118:119], v[0:1], v[14:15] op_sel:[1,0,0]
	v_pk_fma_f32 v[20:21], v[120:121], v[0:1], v[16:17] op_sel_hi:[0,1,1]
	v_pk_fma_f32 v[22:23], v[120:121], v[0:1], v[18:19] op_sel:[1,0,0]
	v_pk_mul_f32 v[4:5], v[8:9], v[122:123] op_sel_hi:[1,0]
	v_pk_mul_f32 v[6:7], v[10:11], v[122:123] op_sel:[0,1]
	v_pk_fma_f32 v[4:5], v[20:21], v[124:125], v[4:5] op_sel_hi:[1,0,1]
	v_pk_fma_f32 v[6:7], v[22:23], v[124:125], v[6:7] op_sel:[0,1,0]
	v_pk_add_f32 v[4:5], v[4:5], v[6:7]
	v_cndmask_b32_e32 v24, v4, v5, vcc
	v_cndmask_b32_e32 v25, v5, v4, vcc
	s_nop 1
	v_add_f32_dpp v26, v25, v24 quad_perm:[1,0,3,2] row_mask:0xf bank_mask:0xf bound_ctrl:1
	s_nop 1
	v_add_f32_dpp v26, v26, v26 quad_perm:[2,3,0,1] row_mask:0xf bank_mask:0xf bound_ctrl:1
	s_nop 1
	v_add_f32_dpp v26, v26, v26 row_ror:4 row_mask:0xf bank_mask:0xf bound_ctrl:1
	s_nop 1
	v_add_f32_dpp v26, v26, v26 row_ror:8 row_mask:0xf bank_mask:0xf bound_ctrl:1
	ds_write_b32 v76, v26 offset:3968
	s_mov_b64 s[6:7], 0
	s_branch .LBB0_1691
